# index top-256 selection rewritten by hand: radix select (2 LDS-histogram passes + scans) replaces 16-step ballot bisection, single compaction sweep
# speedup vs baseline: 1.0236x; 1.0236x over previous
.LBB0_160:
	s_waitcnt lgkmcnt(0)
	s_barrier
	s_add_i32 s2, s27, s22
	s_ashr_i32 s3, s2, 31
	s_lshl_b64 s[2:3], s[2:3], 10
	s_add_u32 s2, s26, s2
	s_addc_u32 s3, s76, s3
	s_cmp_gt_i32 s38, 3
	s_cbranch_scc1 .Lsel_big
	s_cmp_lt_i32 s38, 1
	s_cselect_b64 s[6:7], -1, 0
	s_cmp_lt_i32 s38, 2
	s_cselect_b64 s[78:79], -1, 0
	s_cmp_lt_i32 s38, 3
	s_cselect_b64 s[4:5], -1, 0
	s_branch .LBB0_306
.Lsel_big:
	s_mov_b32 s28, 0x80000000
	s_lshl_b32 s27, s22, 10
	s_add_i32 s27, s27, 0x20000
	v_mov_b32_e32 v84, 1
	v_mov_b32_e32 v100, 0
	v_mov_b32_e32 v101, 0
	v_mov_b32_e32 v102, 0
	v_mov_b32_e32 v103, 0
	v_lshlrev_b32_e32 v86, 4, v34
	v_sub_u32_e32 v87, 0x3f0, v86
	v_add_u32_e32 v86, s27, v86
	v_add_u32_e32 v87, s27, v87
	v_mov_b32_e32 v85, s27
	ds_write_b128 v86, v[100:103]
	ds_read_b32 v0, v114
	ds_read_b32 v1, v114 offset:256
	ds_read_b32 v2, v114 offset:512
	ds_read_b32 v3, v114 offset:768
	ds_read_b32 v4, v114 offset:1024
	ds_read_b32 v5, v114 offset:1280
	ds_read_b32 v6, v114 offset:1536
	ds_read_b32 v7, v114 offset:1792
	s_waitcnt lgkmcnt(0)
	v_cvt_f16_f32_sdwa v0, v0 dst_sel:WORD_1 dst_unused:UNUSED_PAD src0_sel:DWORD
	v_cvt_f16_f32_sdwa v1, v1 dst_sel:WORD_1 dst_unused:UNUSED_PAD src0_sel:DWORD
	s_nop 0
	v_ashrrev_i32_e32 v80, 31, v0
	v_ashrrev_i32_e32 v83, 31, v1
	v_bitop3_b32 v0, v0, v80, s28 bitop3:0x1e
	v_bitop3_b32 v1, v1, v83, s28 bitop3:0x1e
	v_cvt_f16_f32_sdwa v2, v2 dst_sel:WORD_1 dst_unused:UNUSED_PAD src0_sel:DWORD
	v_cvt_f16_f32_sdwa v3, v3 dst_sel:WORD_1 dst_unused:UNUSED_PAD src0_sel:DWORD
	s_nop 0
	v_ashrrev_i32_e32 v80, 31, v2
	v_ashrrev_i32_e32 v83, 31, v3
	v_bitop3_b32 v2, v2, v80, s28 bitop3:0x1e
	v_bitop3_b32 v3, v3, v83, s28 bitop3:0x1e
	v_cvt_f16_f32_sdwa v4, v4 dst_sel:WORD_1 dst_unused:UNUSED_PAD src0_sel:DWORD
	v_cvt_f16_f32_sdwa v5, v5 dst_sel:WORD_1 dst_unused:UNUSED_PAD src0_sel:DWORD
	s_nop 0
	v_ashrrev_i32_e32 v80, 31, v4
	v_ashrrev_i32_e32 v83, 31, v5
	v_bitop3_b32 v4, v4, v80, s28 bitop3:0x1e
	v_bitop3_b32 v5, v5, v83, s28 bitop3:0x1e
	v_cvt_f16_f32_sdwa v6, v6 dst_sel:WORD_1 dst_unused:UNUSED_PAD src0_sel:DWORD
	v_cvt_f16_f32_sdwa v7, v7 dst_sel:WORD_1 dst_unused:UNUSED_PAD src0_sel:DWORD
	s_nop 0
	v_ashrrev_i32_e32 v80, 31, v6
	v_ashrrev_i32_e32 v83, 31, v7
	v_bitop3_b32 v6, v6, v80, s28 bitop3:0x1e
	v_bitop3_b32 v7, v7, v83, s28 bitop3:0x1e
	ds_read_b32 v8, v114 offset:2048
	ds_read_b32 v9, v114 offset:2304
	ds_read_b32 v10, v114 offset:2560
	ds_read_b32 v11, v114 offset:2816
	ds_read_b32 v12, v114 offset:3072
	ds_read_b32 v13, v114 offset:3328
	ds_read_b32 v14, v114 offset:3584
	ds_read_b32 v15, v114 offset:3840
	s_cmp_gt_i32 s38, 6
	s_cbranch_scc1 .Lsel_kb_full0
	s_cmp_gt_i32 s38, 0
	s_cselect_b32 s4, -1, 0
	v_and_b32_e32 v1, s4, v1
	s_cmp_gt_i32 s38, 1
	s_cselect_b32 s4, -1, 0
	v_and_b32_e32 v2, s4, v2
	s_cmp_gt_i32 s38, 2
	s_cselect_b32 s4, -1, 0
	v_and_b32_e32 v3, s4, v3
	s_cmp_gt_i32 s38, 3
	s_cselect_b32 s4, -1, 0
	v_and_b32_e32 v4, s4, v4
	s_cmp_gt_i32 s38, 4
	s_cselect_b32 s4, -1, 0
	v_and_b32_e32 v5, s4, v5
	s_cmp_gt_i32 s38, 5
	s_cselect_b32 s4, -1, 0
	v_and_b32_e32 v6, s4, v6
	s_cmp_gt_i32 s38, 6
	s_cselect_b32 s4, -1, 0
	v_and_b32_e32 v7, s4, v7
	v_bfe_u32 v81, v0, 24, 8
	v_lshl_add_u32 v81, v81, 2, v85
	ds_add_u32 v81, v84
	v_bfe_u32 v82, v1, 24, 8
	v_lshl_add_u32 v82, v82, 2, v85
	ds_add_u32 v82, v84
	v_bfe_u32 v81, v2, 24, 8
	v_lshl_add_u32 v81, v81, 2, v85
	ds_add_u32 v81, v84
	v_bfe_u32 v82, v3, 24, 8
	v_lshl_add_u32 v82, v82, 2, v85
	ds_add_u32 v82, v84
	v_bfe_u32 v81, v4, 24, 8
	v_lshl_add_u32 v81, v81, 2, v85
	ds_add_u32 v81, v84
	v_bfe_u32 v82, v5, 24, 8
	v_lshl_add_u32 v82, v82, 2, v85
	ds_add_u32 v82, v84
	v_bfe_u32 v81, v6, 24, 8
	v_lshl_add_u32 v81, v81, 2, v85
	ds_add_u32 v81, v84
	v_bfe_u32 v82, v7, 24, 8
	v_lshl_add_u32 v82, v82, 2, v85
	ds_add_u32 v82, v84
	s_branch .Lsel_kb_done
.Lsel_kb_full0:
	v_bfe_u32 v81, v0, 24, 8
	v_lshl_add_u32 v81, v81, 2, v85
	ds_add_u32 v81, v84
	v_bfe_u32 v82, v1, 24, 8
	v_lshl_add_u32 v82, v82, 2, v85
	ds_add_u32 v82, v84
	v_bfe_u32 v81, v2, 24, 8
	v_lshl_add_u32 v81, v81, 2, v85
	ds_add_u32 v81, v84
	v_bfe_u32 v82, v3, 24, 8
	v_lshl_add_u32 v82, v82, 2, v85
	ds_add_u32 v82, v84
	v_bfe_u32 v81, v4, 24, 8
	v_lshl_add_u32 v81, v81, 2, v85
	ds_add_u32 v81, v84
	v_bfe_u32 v82, v5, 24, 8
	v_lshl_add_u32 v82, v82, 2, v85
	ds_add_u32 v82, v84
	v_bfe_u32 v81, v6, 24, 8
	v_lshl_add_u32 v81, v81, 2, v85
	ds_add_u32 v81, v84
	v_bfe_u32 v82, v7, 24, 8
	v_lshl_add_u32 v82, v82, 2, v85
	ds_add_u32 v82, v84
	s_cmp_lt_i32 s38, 8
	s_cbranch_scc1 .Lsel_kb_done
	s_waitcnt lgkmcnt(8)
	v_cvt_f16_f32_sdwa v8, v8 dst_sel:WORD_1 dst_unused:UNUSED_PAD src0_sel:DWORD
	v_cvt_f16_f32_sdwa v9, v9 dst_sel:WORD_1 dst_unused:UNUSED_PAD src0_sel:DWORD
	s_nop 0
	v_ashrrev_i32_e32 v80, 31, v8
	v_ashrrev_i32_e32 v83, 31, v9
	v_bitop3_b32 v8, v8, v80, s28 bitop3:0x1e
	v_bitop3_b32 v9, v9, v83, s28 bitop3:0x1e
	v_cvt_f16_f32_sdwa v10, v10 dst_sel:WORD_1 dst_unused:UNUSED_PAD src0_sel:DWORD
	v_cvt_f16_f32_sdwa v11, v11 dst_sel:WORD_1 dst_unused:UNUSED_PAD src0_sel:DWORD
	s_nop 0
	v_ashrrev_i32_e32 v80, 31, v10
	v_ashrrev_i32_e32 v83, 31, v11
	v_bitop3_b32 v10, v10, v80, s28 bitop3:0x1e
	v_bitop3_b32 v11, v11, v83, s28 bitop3:0x1e
	v_cvt_f16_f32_sdwa v12, v12 dst_sel:WORD_1 dst_unused:UNUSED_PAD src0_sel:DWORD
	v_cvt_f16_f32_sdwa v13, v13 dst_sel:WORD_1 dst_unused:UNUSED_PAD src0_sel:DWORD
	s_nop 0
	v_ashrrev_i32_e32 v80, 31, v12
	v_ashrrev_i32_e32 v83, 31, v13
	v_bitop3_b32 v12, v12, v80, s28 bitop3:0x1e
	v_bitop3_b32 v13, v13, v83, s28 bitop3:0x1e
	v_cvt_f16_f32_sdwa v14, v14 dst_sel:WORD_1 dst_unused:UNUSED_PAD src0_sel:DWORD
	v_cvt_f16_f32_sdwa v15, v15 dst_sel:WORD_1 dst_unused:UNUSED_PAD src0_sel:DWORD
	s_nop 0
	v_ashrrev_i32_e32 v80, 31, v14
	v_ashrrev_i32_e32 v83, 31, v15
	v_bitop3_b32 v14, v14, v80, s28 bitop3:0x1e
	v_bitop3_b32 v15, v15, v83, s28 bitop3:0x1e
	ds_read_b32 v16, v114 offset:4096
	ds_read_b32 v17, v114 offset:4352
	ds_read_b32 v18, v114 offset:4608
	ds_read_b32 v19, v114 offset:4864
	ds_read_b32 v20, v114 offset:5120
	ds_read_b32 v21, v114 offset:5376
	ds_read_b32 v22, v114 offset:5632
	ds_read_b32 v23, v114 offset:5888
	s_cmp_gt_i32 s38, 14
	s_cbranch_scc1 .Lsel_kb_full1
	s_cmp_gt_i32 s38, 8
	s_cselect_b32 s4, -1, 0
	v_and_b32_e32 v9, s4, v9
	s_cmp_gt_i32 s38, 9
	s_cselect_b32 s4, -1, 0
	v_and_b32_e32 v10, s4, v10
	s_cmp_gt_i32 s38, 10
	s_cselect_b32 s4, -1, 0
	v_and_b32_e32 v11, s4, v11
	s_cmp_gt_i32 s38, 11
	s_cselect_b32 s4, -1, 0
	v_and_b32_e32 v12, s4, v12
	s_cmp_gt_i32 s38, 12
	s_cselect_b32 s4, -1, 0
	v_and_b32_e32 v13, s4, v13
	s_cmp_gt_i32 s38, 13
	s_cselect_b32 s4, -1, 0
	v_and_b32_e32 v14, s4, v14
	s_cmp_gt_i32 s38, 14
	s_cselect_b32 s4, -1, 0
	v_and_b32_e32 v15, s4, v15
	v_bfe_u32 v81, v8, 24, 8
	v_lshl_add_u32 v81, v81, 2, v85
	ds_add_u32 v81, v84
	v_bfe_u32 v82, v9, 24, 8
	v_lshl_add_u32 v82, v82, 2, v85
	ds_add_u32 v82, v84
	v_bfe_u32 v81, v10, 24, 8
	v_lshl_add_u32 v81, v81, 2, v85
	ds_add_u32 v81, v84
	v_bfe_u32 v82, v11, 24, 8
	v_lshl_add_u32 v82, v82, 2, v85
	ds_add_u32 v82, v84
	v_bfe_u32 v81, v12, 24, 8
	v_lshl_add_u32 v81, v81, 2, v85
	ds_add_u32 v81, v84
	v_bfe_u32 v82, v13, 24, 8
	v_lshl_add_u32 v82, v82, 2, v85
	ds_add_u32 v82, v84
	v_bfe_u32 v81, v14, 24, 8
	v_lshl_add_u32 v81, v81, 2, v85
	ds_add_u32 v81, v84
	v_bfe_u32 v82, v15, 24, 8
	v_lshl_add_u32 v82, v82, 2, v85
	ds_add_u32 v82, v84
	s_branch .Lsel_kb_done
.Lsel_kb_full1:
	v_bfe_u32 v81, v8, 24, 8
	v_lshl_add_u32 v81, v81, 2, v85
	ds_add_u32 v81, v84
	v_bfe_u32 v82, v9, 24, 8
	v_lshl_add_u32 v82, v82, 2, v85
	ds_add_u32 v82, v84
	v_bfe_u32 v81, v10, 24, 8
	v_lshl_add_u32 v81, v81, 2, v85
	ds_add_u32 v81, v84
	v_bfe_u32 v82, v11, 24, 8
	v_lshl_add_u32 v82, v82, 2, v85
	ds_add_u32 v82, v84
	v_bfe_u32 v81, v12, 24, 8
	v_lshl_add_u32 v81, v81, 2, v85
	ds_add_u32 v81, v84
	v_bfe_u32 v82, v13, 24, 8
	v_lshl_add_u32 v82, v82, 2, v85
	ds_add_u32 v82, v84
	v_bfe_u32 v81, v14, 24, 8
	v_lshl_add_u32 v81, v81, 2, v85
	ds_add_u32 v81, v84
	v_bfe_u32 v82, v15, 24, 8
	v_lshl_add_u32 v82, v82, 2, v85
	ds_add_u32 v82, v84
	s_cmp_lt_i32 s38, 16
	s_cbranch_scc1 .Lsel_kb_done
	s_waitcnt lgkmcnt(8)
	v_cvt_f16_f32_sdwa v16, v16 dst_sel:WORD_1 dst_unused:UNUSED_PAD src0_sel:DWORD
	v_cvt_f16_f32_sdwa v17, v17 dst_sel:WORD_1 dst_unused:UNUSED_PAD src0_sel:DWORD
	s_nop 0
	v_ashrrev_i32_e32 v80, 31, v16
	v_ashrrev_i32_e32 v83, 31, v17
	v_bitop3_b32 v16, v16, v80, s28 bitop3:0x1e
	v_bitop3_b32 v17, v17, v83, s28 bitop3:0x1e
	v_cvt_f16_f32_sdwa v18, v18 dst_sel:WORD_1 dst_unused:UNUSED_PAD src0_sel:DWORD
	v_cvt_f16_f32_sdwa v19, v19 dst_sel:WORD_1 dst_unused:UNUSED_PAD src0_sel:DWORD
	s_nop 0
	v_ashrrev_i32_e32 v80, 31, v18
	v_ashrrev_i32_e32 v83, 31, v19
	v_bitop3_b32 v18, v18, v80, s28 bitop3:0x1e
	v_bitop3_b32 v19, v19, v83, s28 bitop3:0x1e
	v_cvt_f16_f32_sdwa v20, v20 dst_sel:WORD_1 dst_unused:UNUSED_PAD src0_sel:DWORD
	v_cvt_f16_f32_sdwa v21, v21 dst_sel:WORD_1 dst_unused:UNUSED_PAD src0_sel:DWORD
	s_nop 0
	v_ashrrev_i32_e32 v80, 31, v20
	v_ashrrev_i32_e32 v83, 31, v21
	v_bitop3_b32 v20, v20, v80, s28 bitop3:0x1e
	v_bitop3_b32 v21, v21, v83, s28 bitop3:0x1e
	v_cvt_f16_f32_sdwa v22, v22 dst_sel:WORD_1 dst_unused:UNUSED_PAD src0_sel:DWORD
	v_cvt_f16_f32_sdwa v23, v23 dst_sel:WORD_1 dst_unused:UNUSED_PAD src0_sel:DWORD
	s_nop 0
	v_ashrrev_i32_e32 v80, 31, v22
	v_ashrrev_i32_e32 v83, 31, v23
	v_bitop3_b32 v22, v22, v80, s28 bitop3:0x1e
	v_bitop3_b32 v23, v23, v83, s28 bitop3:0x1e
	ds_read_b32 v24, v114 offset:6144
	ds_read_b32 v25, v114 offset:6400
	ds_read_b32 v26, v114 offset:6656
	ds_read_b32 v27, v114 offset:6912
	ds_read_b32 v28, v114 offset:7168
	ds_read_b32 v29, v114 offset:7424
	ds_read_b32 v30, v114 offset:7680
	ds_read_b32 v31, v114 offset:7936
	s_cmp_gt_i32 s38, 22
	s_cbranch_scc1 .Lsel_kb_full2
	s_cmp_gt_i32 s38, 16
	s_cselect_b32 s4, -1, 0
	v_and_b32_e32 v17, s4, v17
	s_cmp_gt_i32 s38, 17
	s_cselect_b32 s4, -1, 0
	v_and_b32_e32 v18, s4, v18
	s_cmp_gt_i32 s38, 18
	s_cselect_b32 s4, -1, 0
	v_and_b32_e32 v19, s4, v19
	s_cmp_gt_i32 s38, 19
	s_cselect_b32 s4, -1, 0
	v_and_b32_e32 v20, s4, v20
	s_cmp_gt_i32 s38, 20
	s_cselect_b32 s4, -1, 0
	v_and_b32_e32 v21, s4, v21
	s_cmp_gt_i32 s38, 21
	s_cselect_b32 s4, -1, 0
	v_and_b32_e32 v22, s4, v22
	s_cmp_gt_i32 s38, 22
	s_cselect_b32 s4, -1, 0
	v_and_b32_e32 v23, s4, v23
	v_bfe_u32 v81, v16, 24, 8
	v_lshl_add_u32 v81, v81, 2, v85
	ds_add_u32 v81, v84
	v_bfe_u32 v82, v17, 24, 8
	v_lshl_add_u32 v82, v82, 2, v85
	ds_add_u32 v82, v84
	v_bfe_u32 v81, v18, 24, 8
	v_lshl_add_u32 v81, v81, 2, v85
	ds_add_u32 v81, v84
	v_bfe_u32 v82, v19, 24, 8
	v_lshl_add_u32 v82, v82, 2, v85
	ds_add_u32 v82, v84
	v_bfe_u32 v81, v20, 24, 8
	v_lshl_add_u32 v81, v81, 2, v85
	ds_add_u32 v81, v84
	v_bfe_u32 v82, v21, 24, 8
	v_lshl_add_u32 v82, v82, 2, v85
	ds_add_u32 v82, v84
	v_bfe_u32 v81, v22, 24, 8
	v_lshl_add_u32 v81, v81, 2, v85
	ds_add_u32 v81, v84
	v_bfe_u32 v82, v23, 24, 8
	v_lshl_add_u32 v82, v82, 2, v85
	ds_add_u32 v82, v84
	s_branch .Lsel_kb_done
.Lsel_kb_full2:
	v_bfe_u32 v81, v16, 24, 8
	v_lshl_add_u32 v81, v81, 2, v85
	ds_add_u32 v81, v84
	v_bfe_u32 v82, v17, 24, 8
	v_lshl_add_u32 v82, v82, 2, v85
	ds_add_u32 v82, v84
	v_bfe_u32 v81, v18, 24, 8
	v_lshl_add_u32 v81, v81, 2, v85
	ds_add_u32 v81, v84
	v_bfe_u32 v82, v19, 24, 8
	v_lshl_add_u32 v82, v82, 2, v85
	ds_add_u32 v82, v84
	v_bfe_u32 v81, v20, 24, 8
	v_lshl_add_u32 v81, v81, 2, v85
	ds_add_u32 v81, v84
	v_bfe_u32 v82, v21, 24, 8
	v_lshl_add_u32 v82, v82, 2, v85
	ds_add_u32 v82, v84
	v_bfe_u32 v81, v22, 24, 8
	v_lshl_add_u32 v81, v81, 2, v85
	ds_add_u32 v81, v84
	v_bfe_u32 v82, v23, 24, 8
	v_lshl_add_u32 v82, v82, 2, v85
	ds_add_u32 v82, v84
	s_cmp_lt_i32 s38, 24
	s_cbranch_scc1 .Lsel_kb_done
	s_waitcnt lgkmcnt(8)
	v_cvt_f16_f32_sdwa v24, v24 dst_sel:WORD_1 dst_unused:UNUSED_PAD src0_sel:DWORD
	v_cvt_f16_f32_sdwa v25, v25 dst_sel:WORD_1 dst_unused:UNUSED_PAD src0_sel:DWORD
	s_nop 0
	v_ashrrev_i32_e32 v80, 31, v24
	v_ashrrev_i32_e32 v83, 31, v25
	v_bitop3_b32 v24, v24, v80, s28 bitop3:0x1e
	v_bitop3_b32 v25, v25, v83, s28 bitop3:0x1e
	v_cvt_f16_f32_sdwa v26, v26 dst_sel:WORD_1 dst_unused:UNUSED_PAD src0_sel:DWORD
	v_cvt_f16_f32_sdwa v27, v27 dst_sel:WORD_1 dst_unused:UNUSED_PAD src0_sel:DWORD
	s_nop 0
	v_ashrrev_i32_e32 v80, 31, v26
	v_ashrrev_i32_e32 v83, 31, v27
	v_bitop3_b32 v26, v26, v80, s28 bitop3:0x1e
	v_bitop3_b32 v27, v27, v83, s28 bitop3:0x1e
	v_cvt_f16_f32_sdwa v28, v28 dst_sel:WORD_1 dst_unused:UNUSED_PAD src0_sel:DWORD
	v_cvt_f16_f32_sdwa v29, v29 dst_sel:WORD_1 dst_unused:UNUSED_PAD src0_sel:DWORD
	s_nop 0
	v_ashrrev_i32_e32 v80, 31, v28
	v_ashrrev_i32_e32 v83, 31, v29
	v_bitop3_b32 v28, v28, v80, s28 bitop3:0x1e
	v_bitop3_b32 v29, v29, v83, s28 bitop3:0x1e
	v_cvt_f16_f32_sdwa v30, v30 dst_sel:WORD_1 dst_unused:UNUSED_PAD src0_sel:DWORD
	v_cvt_f16_f32_sdwa v31, v31 dst_sel:WORD_1 dst_unused:UNUSED_PAD src0_sel:DWORD
	s_nop 0
	v_ashrrev_i32_e32 v80, 31, v30
	v_ashrrev_i32_e32 v83, 31, v31
	v_bitop3_b32 v30, v30, v80, s28 bitop3:0x1e
	v_bitop3_b32 v31, v31, v83, s28 bitop3:0x1e
	ds_read_b32 v40, v114 offset:8192
	ds_read_b32 v41, v114 offset:8448
	ds_read_b32 v42, v114 offset:8704
	ds_read_b32 v43, v114 offset:8960
	ds_read_b32 v44, v114 offset:9216
	ds_read_b32 v45, v114 offset:9472
	ds_read_b32 v46, v114 offset:9728
	ds_read_b32 v47, v114 offset:9984
	s_cmp_gt_i32 s38, 30
	s_cbranch_scc1 .Lsel_kb_full3
	s_cmp_gt_i32 s38, 24
	s_cselect_b32 s4, -1, 0
	v_and_b32_e32 v25, s4, v25
	s_cmp_gt_i32 s38, 25
	s_cselect_b32 s4, -1, 0
	v_and_b32_e32 v26, s4, v26
	s_cmp_gt_i32 s38, 26
	s_cselect_b32 s4, -1, 0
	v_and_b32_e32 v27, s4, v27
	s_cmp_gt_i32 s38, 27
	s_cselect_b32 s4, -1, 0
	v_and_b32_e32 v28, s4, v28
	s_cmp_gt_i32 s38, 28
	s_cselect_b32 s4, -1, 0
	v_and_b32_e32 v29, s4, v29
	s_cmp_gt_i32 s38, 29
	s_cselect_b32 s4, -1, 0
	v_and_b32_e32 v30, s4, v30
	s_cmp_gt_i32 s38, 30
	s_cselect_b32 s4, -1, 0
	v_and_b32_e32 v31, s4, v31
	v_bfe_u32 v81, v24, 24, 8
	v_lshl_add_u32 v81, v81, 2, v85
	ds_add_u32 v81, v84
	v_bfe_u32 v82, v25, 24, 8
	v_lshl_add_u32 v82, v82, 2, v85
	ds_add_u32 v82, v84
	v_bfe_u32 v81, v26, 24, 8
	v_lshl_add_u32 v81, v81, 2, v85
	ds_add_u32 v81, v84
	v_bfe_u32 v82, v27, 24, 8
	v_lshl_add_u32 v82, v82, 2, v85
	ds_add_u32 v82, v84
	v_bfe_u32 v81, v28, 24, 8
	v_lshl_add_u32 v81, v81, 2, v85
	ds_add_u32 v81, v84
	v_bfe_u32 v82, v29, 24, 8
	v_lshl_add_u32 v82, v82, 2, v85
	ds_add_u32 v82, v84
	v_bfe_u32 v81, v30, 24, 8
	v_lshl_add_u32 v81, v81, 2, v85
	ds_add_u32 v81, v84
	v_bfe_u32 v82, v31, 24, 8
	v_lshl_add_u32 v82, v82, 2, v85
	ds_add_u32 v82, v84
	s_branch .Lsel_kb_done
.Lsel_kb_full3:
	v_bfe_u32 v81, v24, 24, 8
	v_lshl_add_u32 v81, v81, 2, v85
	ds_add_u32 v81, v84
	v_bfe_u32 v82, v25, 24, 8
	v_lshl_add_u32 v82, v82, 2, v85
	ds_add_u32 v82, v84
	v_bfe_u32 v81, v26, 24, 8
	v_lshl_add_u32 v81, v81, 2, v85
	ds_add_u32 v81, v84
	v_bfe_u32 v82, v27, 24, 8
	v_lshl_add_u32 v82, v82, 2, v85
	ds_add_u32 v82, v84
	v_bfe_u32 v81, v28, 24, 8
	v_lshl_add_u32 v81, v81, 2, v85
	ds_add_u32 v81, v84
	v_bfe_u32 v82, v29, 24, 8
	v_lshl_add_u32 v82, v82, 2, v85
	ds_add_u32 v82, v84
	v_bfe_u32 v81, v30, 24, 8
	v_lshl_add_u32 v81, v81, 2, v85
	ds_add_u32 v81, v84
	v_bfe_u32 v82, v31, 24, 8
	v_lshl_add_u32 v82, v82, 2, v85
	ds_add_u32 v82, v84
	s_cmp_lt_i32 s38, 32
	s_cbranch_scc1 .Lsel_kb_done
	s_waitcnt lgkmcnt(8)
	v_cvt_f16_f32_sdwa v40, v40 dst_sel:WORD_1 dst_unused:UNUSED_PAD src0_sel:DWORD
	v_cvt_f16_f32_sdwa v41, v41 dst_sel:WORD_1 dst_unused:UNUSED_PAD src0_sel:DWORD
	s_nop 0
	v_ashrrev_i32_e32 v80, 31, v40
	v_ashrrev_i32_e32 v83, 31, v41
	v_bitop3_b32 v40, v40, v80, s28 bitop3:0x1e
	v_bitop3_b32 v41, v41, v83, s28 bitop3:0x1e
	v_cvt_f16_f32_sdwa v42, v42 dst_sel:WORD_1 dst_unused:UNUSED_PAD src0_sel:DWORD
	v_cvt_f16_f32_sdwa v43, v43 dst_sel:WORD_1 dst_unused:UNUSED_PAD src0_sel:DWORD
	s_nop 0
	v_ashrrev_i32_e32 v80, 31, v42
	v_ashrrev_i32_e32 v83, 31, v43
	v_bitop3_b32 v42, v42, v80, s28 bitop3:0x1e
	v_bitop3_b32 v43, v43, v83, s28 bitop3:0x1e
	v_cvt_f16_f32_sdwa v44, v44 dst_sel:WORD_1 dst_unused:UNUSED_PAD src0_sel:DWORD
	v_cvt_f16_f32_sdwa v45, v45 dst_sel:WORD_1 dst_unused:UNUSED_PAD src0_sel:DWORD
	s_nop 0
	v_ashrrev_i32_e32 v80, 31, v44
	v_ashrrev_i32_e32 v83, 31, v45
	v_bitop3_b32 v44, v44, v80, s28 bitop3:0x1e
	v_bitop3_b32 v45, v45, v83, s28 bitop3:0x1e
	v_cvt_f16_f32_sdwa v46, v46 dst_sel:WORD_1 dst_unused:UNUSED_PAD src0_sel:DWORD
	v_cvt_f16_f32_sdwa v47, v47 dst_sel:WORD_1 dst_unused:UNUSED_PAD src0_sel:DWORD
	s_nop 0
	v_ashrrev_i32_e32 v80, 31, v46
	v_ashrrev_i32_e32 v83, 31, v47
	v_bitop3_b32 v46, v46, v80, s28 bitop3:0x1e
	v_bitop3_b32 v47, v47, v83, s28 bitop3:0x1e
	ds_read_b32 v48, v114 offset:10240
	ds_read_b32 v49, v114 offset:10496
	ds_read_b32 v50, v114 offset:10752
	ds_read_b32 v51, v114 offset:11008
	ds_read_b32 v52, v114 offset:11264
	ds_read_b32 v53, v114 offset:11520
	ds_read_b32 v54, v114 offset:11776
	ds_read_b32 v55, v114 offset:12032
	s_cmp_gt_i32 s38, 38
	s_cbranch_scc1 .Lsel_kb_full4
	s_cmp_gt_i32 s38, 32
	s_cselect_b32 s4, -1, 0
	v_and_b32_e32 v41, s4, v41
	s_cmp_gt_i32 s38, 33
	s_cselect_b32 s4, -1, 0
	v_and_b32_e32 v42, s4, v42
	s_cmp_gt_i32 s38, 34
	s_cselect_b32 s4, -1, 0
	v_and_b32_e32 v43, s4, v43
	s_cmp_gt_i32 s38, 35
	s_cselect_b32 s4, -1, 0
	v_and_b32_e32 v44, s4, v44
	s_cmp_gt_i32 s38, 36
	s_cselect_b32 s4, -1, 0
	v_and_b32_e32 v45, s4, v45
	s_cmp_gt_i32 s38, 37
	s_cselect_b32 s4, -1, 0
	v_and_b32_e32 v46, s4, v46
	s_cmp_gt_i32 s38, 38
	s_cselect_b32 s4, -1, 0
	v_and_b32_e32 v47, s4, v47
	v_bfe_u32 v81, v40, 24, 8
	v_lshl_add_u32 v81, v81, 2, v85
	ds_add_u32 v81, v84
	v_bfe_u32 v82, v41, 24, 8
	v_lshl_add_u32 v82, v82, 2, v85
	ds_add_u32 v82, v84
	v_bfe_u32 v81, v42, 24, 8
	v_lshl_add_u32 v81, v81, 2, v85
	ds_add_u32 v81, v84
	v_bfe_u32 v82, v43, 24, 8
	v_lshl_add_u32 v82, v82, 2, v85
	ds_add_u32 v82, v84
	v_bfe_u32 v81, v44, 24, 8
	v_lshl_add_u32 v81, v81, 2, v85
	ds_add_u32 v81, v84
	v_bfe_u32 v82, v45, 24, 8
	v_lshl_add_u32 v82, v82, 2, v85
	ds_add_u32 v82, v84
	v_bfe_u32 v81, v46, 24, 8
	v_lshl_add_u32 v81, v81, 2, v85
	ds_add_u32 v81, v84
	v_bfe_u32 v82, v47, 24, 8
	v_lshl_add_u32 v82, v82, 2, v85
	ds_add_u32 v82, v84
	s_branch .Lsel_kb_done
.Lsel_kb_full4:
	v_bfe_u32 v81, v40, 24, 8
	v_lshl_add_u32 v81, v81, 2, v85
	ds_add_u32 v81, v84
	v_bfe_u32 v82, v41, 24, 8
	v_lshl_add_u32 v82, v82, 2, v85
	ds_add_u32 v82, v84
	v_bfe_u32 v81, v42, 24, 8
	v_lshl_add_u32 v81, v81, 2, v85
	ds_add_u32 v81, v84
	v_bfe_u32 v82, v43, 24, 8
	v_lshl_add_u32 v82, v82, 2, v85
	ds_add_u32 v82, v84
	v_bfe_u32 v81, v44, 24, 8
	v_lshl_add_u32 v81, v81, 2, v85
	ds_add_u32 v81, v84
	v_bfe_u32 v82, v45, 24, 8
	v_lshl_add_u32 v82, v82, 2, v85
	ds_add_u32 v82, v84
	v_bfe_u32 v81, v46, 24, 8
	v_lshl_add_u32 v81, v81, 2, v85
	ds_add_u32 v81, v84
	v_bfe_u32 v82, v47, 24, 8
	v_lshl_add_u32 v82, v82, 2, v85
	ds_add_u32 v82, v84
	s_cmp_lt_i32 s38, 40
	s_cbranch_scc1 .Lsel_kb_done
	s_waitcnt lgkmcnt(8)
	v_cvt_f16_f32_sdwa v48, v48 dst_sel:WORD_1 dst_unused:UNUSED_PAD src0_sel:DWORD
	v_cvt_f16_f32_sdwa v49, v49 dst_sel:WORD_1 dst_unused:UNUSED_PAD src0_sel:DWORD
	s_nop 0
	v_ashrrev_i32_e32 v80, 31, v48
	v_ashrrev_i32_e32 v83, 31, v49
	v_bitop3_b32 v48, v48, v80, s28 bitop3:0x1e
	v_bitop3_b32 v49, v49, v83, s28 bitop3:0x1e
	v_cvt_f16_f32_sdwa v50, v50 dst_sel:WORD_1 dst_unused:UNUSED_PAD src0_sel:DWORD
	v_cvt_f16_f32_sdwa v51, v51 dst_sel:WORD_1 dst_unused:UNUSED_PAD src0_sel:DWORD
	s_nop 0
	v_ashrrev_i32_e32 v80, 31, v50
	v_ashrrev_i32_e32 v83, 31, v51
	v_bitop3_b32 v50, v50, v80, s28 bitop3:0x1e
	v_bitop3_b32 v51, v51, v83, s28 bitop3:0x1e
	v_cvt_f16_f32_sdwa v52, v52 dst_sel:WORD_1 dst_unused:UNUSED_PAD src0_sel:DWORD
	v_cvt_f16_f32_sdwa v53, v53 dst_sel:WORD_1 dst_unused:UNUSED_PAD src0_sel:DWORD
	s_nop 0
	v_ashrrev_i32_e32 v80, 31, v52
	v_ashrrev_i32_e32 v83, 31, v53
	v_bitop3_b32 v52, v52, v80, s28 bitop3:0x1e
	v_bitop3_b32 v53, v53, v83, s28 bitop3:0x1e
	v_cvt_f16_f32_sdwa v54, v54 dst_sel:WORD_1 dst_unused:UNUSED_PAD src0_sel:DWORD
	v_cvt_f16_f32_sdwa v55, v55 dst_sel:WORD_1 dst_unused:UNUSED_PAD src0_sel:DWORD
	s_nop 0
	v_ashrrev_i32_e32 v80, 31, v54
	v_ashrrev_i32_e32 v83, 31, v55
	v_bitop3_b32 v54, v54, v80, s28 bitop3:0x1e
	v_bitop3_b32 v55, v55, v83, s28 bitop3:0x1e
	ds_read_b32 v56, v114 offset:12288
	ds_read_b32 v57, v114 offset:12544
	ds_read_b32 v58, v114 offset:12800
	ds_read_b32 v59, v114 offset:13056
	ds_read_b32 v60, v114 offset:13312
	ds_read_b32 v61, v114 offset:13568
	ds_read_b32 v62, v114 offset:13824
	ds_read_b32 v63, v114 offset:14080
	s_cmp_gt_i32 s38, 46
	s_cbranch_scc1 .Lsel_kb_full5
	s_cmp_gt_i32 s38, 40
	s_cselect_b32 s4, -1, 0
	v_and_b32_e32 v49, s4, v49
	s_cmp_gt_i32 s38, 41
	s_cselect_b32 s4, -1, 0
	v_and_b32_e32 v50, s4, v50
	s_cmp_gt_i32 s38, 42
	s_cselect_b32 s4, -1, 0
	v_and_b32_e32 v51, s4, v51
	s_cmp_gt_i32 s38, 43
	s_cselect_b32 s4, -1, 0
	v_and_b32_e32 v52, s4, v52
	s_cmp_gt_i32 s38, 44
	s_cselect_b32 s4, -1, 0
	v_and_b32_e32 v53, s4, v53
	s_cmp_gt_i32 s38, 45
	s_cselect_b32 s4, -1, 0
	v_and_b32_e32 v54, s4, v54
	s_cmp_gt_i32 s38, 46
	s_cselect_b32 s4, -1, 0
	v_and_b32_e32 v55, s4, v55
	v_bfe_u32 v81, v48, 24, 8
	v_lshl_add_u32 v81, v81, 2, v85
	ds_add_u32 v81, v84
	v_bfe_u32 v82, v49, 24, 8
	v_lshl_add_u32 v82, v82, 2, v85
	ds_add_u32 v82, v84
	v_bfe_u32 v81, v50, 24, 8
	v_lshl_add_u32 v81, v81, 2, v85
	ds_add_u32 v81, v84
	v_bfe_u32 v82, v51, 24, 8
	v_lshl_add_u32 v82, v82, 2, v85
	ds_add_u32 v82, v84
	v_bfe_u32 v81, v52, 24, 8
	v_lshl_add_u32 v81, v81, 2, v85
	ds_add_u32 v81, v84
	v_bfe_u32 v82, v53, 24, 8
	v_lshl_add_u32 v82, v82, 2, v85
	ds_add_u32 v82, v84
	v_bfe_u32 v81, v54, 24, 8
	v_lshl_add_u32 v81, v81, 2, v85
	ds_add_u32 v81, v84
	v_bfe_u32 v82, v55, 24, 8
	v_lshl_add_u32 v82, v82, 2, v85
	ds_add_u32 v82, v84
	s_branch .Lsel_kb_done
.Lsel_kb_full5:
	v_bfe_u32 v81, v48, 24, 8
	v_lshl_add_u32 v81, v81, 2, v85
	ds_add_u32 v81, v84
	v_bfe_u32 v82, v49, 24, 8
	v_lshl_add_u32 v82, v82, 2, v85
	ds_add_u32 v82, v84
	v_bfe_u32 v81, v50, 24, 8
	v_lshl_add_u32 v81, v81, 2, v85
	ds_add_u32 v81, v84
	v_bfe_u32 v82, v51, 24, 8
	v_lshl_add_u32 v82, v82, 2, v85
	ds_add_u32 v82, v84
	v_bfe_u32 v81, v52, 24, 8
	v_lshl_add_u32 v81, v81, 2, v85
	ds_add_u32 v81, v84
	v_bfe_u32 v82, v53, 24, 8
	v_lshl_add_u32 v82, v82, 2, v85
	ds_add_u32 v82, v84
	v_bfe_u32 v81, v54, 24, 8
	v_lshl_add_u32 v81, v81, 2, v85
	ds_add_u32 v81, v84
	v_bfe_u32 v82, v55, 24, 8
	v_lshl_add_u32 v82, v82, 2, v85
	ds_add_u32 v82, v84
	s_cmp_lt_i32 s38, 48
	s_cbranch_scc1 .Lsel_kb_done
	s_waitcnt lgkmcnt(8)
	v_cvt_f16_f32_sdwa v56, v56 dst_sel:WORD_1 dst_unused:UNUSED_PAD src0_sel:DWORD
	v_cvt_f16_f32_sdwa v57, v57 dst_sel:WORD_1 dst_unused:UNUSED_PAD src0_sel:DWORD
	s_nop 0
	v_ashrrev_i32_e32 v80, 31, v56
	v_ashrrev_i32_e32 v83, 31, v57
	v_bitop3_b32 v56, v56, v80, s28 bitop3:0x1e
	v_bitop3_b32 v57, v57, v83, s28 bitop3:0x1e
	v_cvt_f16_f32_sdwa v58, v58 dst_sel:WORD_1 dst_unused:UNUSED_PAD src0_sel:DWORD
	v_cvt_f16_f32_sdwa v59, v59 dst_sel:WORD_1 dst_unused:UNUSED_PAD src0_sel:DWORD
	s_nop 0
	v_ashrrev_i32_e32 v80, 31, v58
	v_ashrrev_i32_e32 v83, 31, v59
	v_bitop3_b32 v58, v58, v80, s28 bitop3:0x1e
	v_bitop3_b32 v59, v59, v83, s28 bitop3:0x1e
	v_cvt_f16_f32_sdwa v60, v60 dst_sel:WORD_1 dst_unused:UNUSED_PAD src0_sel:DWORD
	v_cvt_f16_f32_sdwa v61, v61 dst_sel:WORD_1 dst_unused:UNUSED_PAD src0_sel:DWORD
	s_nop 0
	v_ashrrev_i32_e32 v80, 31, v60
	v_ashrrev_i32_e32 v83, 31, v61
	v_bitop3_b32 v60, v60, v80, s28 bitop3:0x1e
	v_bitop3_b32 v61, v61, v83, s28 bitop3:0x1e
	v_cvt_f16_f32_sdwa v62, v62 dst_sel:WORD_1 dst_unused:UNUSED_PAD src0_sel:DWORD
	v_cvt_f16_f32_sdwa v63, v63 dst_sel:WORD_1 dst_unused:UNUSED_PAD src0_sel:DWORD
	s_nop 0
	v_ashrrev_i32_e32 v80, 31, v62
	v_ashrrev_i32_e32 v83, 31, v63
	v_bitop3_b32 v62, v62, v80, s28 bitop3:0x1e
	v_bitop3_b32 v63, v63, v83, s28 bitop3:0x1e
	ds_read_b32 v64, v114 offset:14336
	ds_read_b32 v65, v114 offset:14592
	ds_read_b32 v66, v114 offset:14848
	ds_read_b32 v67, v114 offset:15104
	ds_read_b32 v68, v114 offset:15360
	ds_read_b32 v69, v114 offset:15616
	ds_read_b32 v70, v114 offset:15872
	ds_read_b32 v71, v114 offset:16128
	s_cmp_gt_i32 s38, 54
	s_cbranch_scc1 .Lsel_kb_full6
	s_cmp_gt_i32 s38, 48
	s_cselect_b32 s4, -1, 0
	v_and_b32_e32 v57, s4, v57
	s_cmp_gt_i32 s38, 49
	s_cselect_b32 s4, -1, 0
	v_and_b32_e32 v58, s4, v58
	s_cmp_gt_i32 s38, 50
	s_cselect_b32 s4, -1, 0
	v_and_b32_e32 v59, s4, v59
	s_cmp_gt_i32 s38, 51
	s_cselect_b32 s4, -1, 0
	v_and_b32_e32 v60, s4, v60
	s_cmp_gt_i32 s38, 52
	s_cselect_b32 s4, -1, 0
	v_and_b32_e32 v61, s4, v61
	s_cmp_gt_i32 s38, 53
	s_cselect_b32 s4, -1, 0
	v_and_b32_e32 v62, s4, v62
	s_cmp_gt_i32 s38, 54
	s_cselect_b32 s4, -1, 0
	v_and_b32_e32 v63, s4, v63
	v_bfe_u32 v81, v56, 24, 8
	v_lshl_add_u32 v81, v81, 2, v85
	ds_add_u32 v81, v84
	v_bfe_u32 v82, v57, 24, 8
	v_lshl_add_u32 v82, v82, 2, v85
	ds_add_u32 v82, v84
	v_bfe_u32 v81, v58, 24, 8
	v_lshl_add_u32 v81, v81, 2, v85
	ds_add_u32 v81, v84
	v_bfe_u32 v82, v59, 24, 8
	v_lshl_add_u32 v82, v82, 2, v85
	ds_add_u32 v82, v84
	v_bfe_u32 v81, v60, 24, 8
	v_lshl_add_u32 v81, v81, 2, v85
	ds_add_u32 v81, v84
	v_bfe_u32 v82, v61, 24, 8
	v_lshl_add_u32 v82, v82, 2, v85
	ds_add_u32 v82, v84
	v_bfe_u32 v81, v62, 24, 8
	v_lshl_add_u32 v81, v81, 2, v85
	ds_add_u32 v81, v84
	v_bfe_u32 v82, v63, 24, 8
	v_lshl_add_u32 v82, v82, 2, v85
	ds_add_u32 v82, v84
	s_branch .Lsel_kb_done
.Lsel_kb_full6:
	v_bfe_u32 v81, v56, 24, 8
	v_lshl_add_u32 v81, v81, 2, v85
	ds_add_u32 v81, v84
	v_bfe_u32 v82, v57, 24, 8
	v_lshl_add_u32 v82, v82, 2, v85
	ds_add_u32 v82, v84
	v_bfe_u32 v81, v58, 24, 8
	v_lshl_add_u32 v81, v81, 2, v85
	ds_add_u32 v81, v84
	v_bfe_u32 v82, v59, 24, 8
	v_lshl_add_u32 v82, v82, 2, v85
	ds_add_u32 v82, v84
	v_bfe_u32 v81, v60, 24, 8
	v_lshl_add_u32 v81, v81, 2, v85
	ds_add_u32 v81, v84
	v_bfe_u32 v82, v61, 24, 8
	v_lshl_add_u32 v82, v82, 2, v85
	ds_add_u32 v82, v84
	v_bfe_u32 v81, v62, 24, 8
	v_lshl_add_u32 v81, v81, 2, v85
	ds_add_u32 v81, v84
	v_bfe_u32 v82, v63, 24, 8
	v_lshl_add_u32 v82, v82, 2, v85
	ds_add_u32 v82, v84
	s_cmp_lt_i32 s38, 56
	s_cbranch_scc1 .Lsel_kb_done
	s_waitcnt lgkmcnt(8)
	v_cvt_f16_f32_sdwa v64, v64 dst_sel:WORD_1 dst_unused:UNUSED_PAD src0_sel:DWORD
	v_cvt_f16_f32_sdwa v65, v65 dst_sel:WORD_1 dst_unused:UNUSED_PAD src0_sel:DWORD
	s_nop 0
	v_ashrrev_i32_e32 v80, 31, v64
	v_ashrrev_i32_e32 v83, 31, v65
	v_bitop3_b32 v64, v64, v80, s28 bitop3:0x1e
	v_bitop3_b32 v65, v65, v83, s28 bitop3:0x1e
	v_cvt_f16_f32_sdwa v66, v66 dst_sel:WORD_1 dst_unused:UNUSED_PAD src0_sel:DWORD
	v_cvt_f16_f32_sdwa v67, v67 dst_sel:WORD_1 dst_unused:UNUSED_PAD src0_sel:DWORD
	s_nop 0
	v_ashrrev_i32_e32 v80, 31, v66
	v_ashrrev_i32_e32 v83, 31, v67
	v_bitop3_b32 v66, v66, v80, s28 bitop3:0x1e
	v_bitop3_b32 v67, v67, v83, s28 bitop3:0x1e
	v_cvt_f16_f32_sdwa v68, v68 dst_sel:WORD_1 dst_unused:UNUSED_PAD src0_sel:DWORD
	v_cvt_f16_f32_sdwa v69, v69 dst_sel:WORD_1 dst_unused:UNUSED_PAD src0_sel:DWORD
	s_nop 0
	v_ashrrev_i32_e32 v80, 31, v68
	v_ashrrev_i32_e32 v83, 31, v69
	v_bitop3_b32 v68, v68, v80, s28 bitop3:0x1e
	v_bitop3_b32 v69, v69, v83, s28 bitop3:0x1e
	v_cvt_f16_f32_sdwa v70, v70 dst_sel:WORD_1 dst_unused:UNUSED_PAD src0_sel:DWORD
	v_cvt_f16_f32_sdwa v71, v71 dst_sel:WORD_1 dst_unused:UNUSED_PAD src0_sel:DWORD
	s_nop 0
	v_ashrrev_i32_e32 v80, 31, v70
	v_ashrrev_i32_e32 v83, 31, v71
	v_bitop3_b32 v70, v70, v80, s28 bitop3:0x1e
	v_bitop3_b32 v71, v71, v83, s28 bitop3:0x1e
	s_cmp_gt_i32 s38, 62
	s_cbranch_scc1 .Lsel_kb_full7
	s_cmp_gt_i32 s38, 56
	s_cselect_b32 s4, -1, 0
	v_and_b32_e32 v65, s4, v65
	s_cmp_gt_i32 s38, 57
	s_cselect_b32 s4, -1, 0
	v_and_b32_e32 v66, s4, v66
	s_cmp_gt_i32 s38, 58
	s_cselect_b32 s4, -1, 0
	v_and_b32_e32 v67, s4, v67
	s_cmp_gt_i32 s38, 59
	s_cselect_b32 s4, -1, 0
	v_and_b32_e32 v68, s4, v68
	s_cmp_gt_i32 s38, 60
	s_cselect_b32 s4, -1, 0
	v_and_b32_e32 v69, s4, v69
	s_cmp_gt_i32 s38, 61
	s_cselect_b32 s4, -1, 0
	v_and_b32_e32 v70, s4, v70
	s_cmp_gt_i32 s38, 62
	s_cselect_b32 s4, -1, 0
	v_and_b32_e32 v71, s4, v71
	v_bfe_u32 v81, v64, 24, 8
	v_lshl_add_u32 v81, v81, 2, v85
	ds_add_u32 v81, v84
	v_bfe_u32 v82, v65, 24, 8
	v_lshl_add_u32 v82, v82, 2, v85
	ds_add_u32 v82, v84
	v_bfe_u32 v81, v66, 24, 8
	v_lshl_add_u32 v81, v81, 2, v85
	ds_add_u32 v81, v84
	v_bfe_u32 v82, v67, 24, 8
	v_lshl_add_u32 v82, v82, 2, v85
	ds_add_u32 v82, v84
	v_bfe_u32 v81, v68, 24, 8
	v_lshl_add_u32 v81, v81, 2, v85
	ds_add_u32 v81, v84
	v_bfe_u32 v82, v69, 24, 8
	v_lshl_add_u32 v82, v82, 2, v85
	ds_add_u32 v82, v84
	v_bfe_u32 v81, v70, 24, 8
	v_lshl_add_u32 v81, v81, 2, v85
	ds_add_u32 v81, v84
	v_bfe_u32 v82, v71, 24, 8
	v_lshl_add_u32 v82, v82, 2, v85
	ds_add_u32 v82, v84
	s_branch .Lsel_kb_done
.Lsel_kb_full7:
	v_bfe_u32 v81, v64, 24, 8
	v_lshl_add_u32 v81, v81, 2, v85
	ds_add_u32 v81, v84
	v_bfe_u32 v82, v65, 24, 8
	v_lshl_add_u32 v82, v82, 2, v85
	ds_add_u32 v82, v84
	v_bfe_u32 v81, v66, 24, 8
	v_lshl_add_u32 v81, v81, 2, v85
	ds_add_u32 v81, v84
	v_bfe_u32 v82, v67, 24, 8
	v_lshl_add_u32 v82, v82, 2, v85
	ds_add_u32 v82, v84
	v_bfe_u32 v81, v68, 24, 8
	v_lshl_add_u32 v81, v81, 2, v85
	ds_add_u32 v81, v84
	v_bfe_u32 v82, v69, 24, 8
	v_lshl_add_u32 v82, v82, 2, v85
	ds_add_u32 v82, v84
	v_bfe_u32 v81, v70, 24, 8
	v_lshl_add_u32 v81, v81, 2, v85
	ds_add_u32 v81, v84
	v_bfe_u32 v82, v71, 24, 8
	v_lshl_add_u32 v82, v82, 2, v85
	ds_add_u32 v82, v84
.Lsel_kb_done:
	s_movk_i32 s29, 0x100
	s_waitcnt lgkmcnt(0)
	ds_read_b128 v[88:91], v87
	s_waitcnt lgkmcnt(0)
	ds_write_b128 v86, v[100:103]
	v_add3_u32 v92, v88, v89, v90
	v_add_u32_e32 v92, v92, v91
	v_mov_b32_e32 v93, v92
	s_nop 1
	v_add_u32_dpp v93, v93, v93 row_shr:1 row_mask:0xf bank_mask:0xf
	s_nop 1
	v_add_u32_dpp v93, v93, v93 row_shr:2 row_mask:0xf bank_mask:0xf
	s_nop 1
	v_add_u32_dpp v93, v93, v93 row_shr:4 row_mask:0xf bank_mask:0xf
	s_nop 1
	v_add_u32_dpp v93, v93, v93 row_shr:8 row_mask:0xf bank_mask:0xf
	s_nop 1
	v_readlane_b32 s40, v93, 15
	v_readlane_b32 s41, v93, 31
	v_readlane_b32 s42, v93, 47
	s_add_i32 s41, s40, s41
	s_add_i32 s42, s41, s42
	s_mov_b32 exec_lo, 0xffff0000
	s_mov_b32 exec_hi, 0
	v_add_u32_e32 v93, s40, v93
	s_mov_b32 exec_lo, 0
	s_mov_b32 exec_hi, 0xffff
	v_add_u32_e32 v93, s41, v93
	s_mov_b32 exec_hi, 0xffff0000
	v_add_u32_e32 v93, s42, v93
	s_mov_b64 exec, -1
	v_sub_u32_e32 v94, v93, v92
	v_add_u32_e32 v95, v94, v91
	v_add_u32_e32 v96, v95, v90
	v_add_u32_e32 v97, v96, v89
	v_cmp_gt_u32_e32 vcc, s29, v94
	s_bcnt1_i32_b64 s30, vcc
	v_cmp_gt_u32_e32 vcc, s29, v95
	s_bcnt1_i32_b64 s4, vcc
	s_add_i32 s30, s30, s4
	v_cmp_gt_u32_e32 vcc, s29, v96
	s_bcnt1_i32_b64 s4, vcc
	s_add_i32 s30, s30, s4
	v_cmp_gt_u32_e32 vcc, s29, v97
	s_bcnt1_i32_b64 s4, vcc
	s_add_i32 s30, s30, s4
	s_add_i32 s30, s30, -1
	s_lshr_b32 s5, s30, 2
	s_and_b32 s6, s30, 3
	s_sub_i32 s34, 0xff, s30
	s_nop 3
	v_readlane_b32 s40, v94, s5
	v_readlane_b32 s41, v95, s5
	v_readlane_b32 s42, v96, s5
	v_readlane_b32 s43, v97, s5
	s_cmp_eq_u32 s6, 1
	s_cselect_b32 s40, s41, s40
	s_cmp_eq_u32 s6, 2
	s_cselect_b32 s40, s42, s40
	s_cmp_eq_u32 s6, 3
	s_cselect_b32 s40, s43, s40
	s_mov_b32 s35, s40
	s_sub_i32 s29, 0x100, s35
	s_lshl_b32 s36, s34, 24
	v_subrev_u32_e32 v81, s36, v0
	v_cmp_gt_u32_e32 vcc, 0x1000000, v81
	v_bfe_u32 v82, v81, 16, 8
	v_lshl_add_u32 v82, v82, 2, v85
	s_mov_b64 exec, vcc
	ds_add_u32 v82, v84
	s_mov_b64 exec, -1
	v_subrev_u32_e32 v81, s36, v1
	v_cmp_gt_u32_e32 vcc, 0x1000000, v81
	v_bfe_u32 v82, v81, 16, 8
	v_lshl_add_u32 v82, v82, 2, v85
	s_mov_b64 exec, vcc
	ds_add_u32 v82, v84
	s_mov_b64 exec, -1
	v_subrev_u32_e32 v81, s36, v2
	v_cmp_gt_u32_e32 vcc, 0x1000000, v81
	v_bfe_u32 v82, v81, 16, 8
	v_lshl_add_u32 v82, v82, 2, v85
	s_mov_b64 exec, vcc
	ds_add_u32 v82, v84
	s_mov_b64 exec, -1
	v_subrev_u32_e32 v81, s36, v3
	v_cmp_gt_u32_e32 vcc, 0x1000000, v81
	v_bfe_u32 v82, v81, 16, 8
	v_lshl_add_u32 v82, v82, 2, v85
	s_mov_b64 exec, vcc
	ds_add_u32 v82, v84
	s_mov_b64 exec, -1
	v_subrev_u32_e32 v81, s36, v4
	v_cmp_gt_u32_e32 vcc, 0x1000000, v81
	v_bfe_u32 v82, v81, 16, 8
	v_lshl_add_u32 v82, v82, 2, v85
	s_mov_b64 exec, vcc
	ds_add_u32 v82, v84
	s_mov_b64 exec, -1
	v_subrev_u32_e32 v81, s36, v5
	v_cmp_gt_u32_e32 vcc, 0x1000000, v81
	v_bfe_u32 v82, v81, 16, 8
	v_lshl_add_u32 v82, v82, 2, v85
	s_mov_b64 exec, vcc
	ds_add_u32 v82, v84
	s_mov_b64 exec, -1
	v_subrev_u32_e32 v81, s36, v6
	v_cmp_gt_u32_e32 vcc, 0x1000000, v81
	v_bfe_u32 v82, v81, 16, 8
	v_lshl_add_u32 v82, v82, 2, v85
	s_mov_b64 exec, vcc
	ds_add_u32 v82, v84
	s_mov_b64 exec, -1
	v_subrev_u32_e32 v81, s36, v7
	v_cmp_gt_u32_e32 vcc, 0x1000000, v81
	v_bfe_u32 v82, v81, 16, 8
	v_lshl_add_u32 v82, v82, 2, v85
	s_mov_b64 exec, vcc
	ds_add_u32 v82, v84
	s_mov_b64 exec, -1
	s_cmp_lt_i32 s38, 8
	s_cbranch_scc1 .Lsel_p2_done
	v_subrev_u32_e32 v81, s36, v8
	v_cmp_gt_u32_e32 vcc, 0x1000000, v81
	v_bfe_u32 v82, v81, 16, 8
	v_lshl_add_u32 v82, v82, 2, v85
	s_mov_b64 exec, vcc
	ds_add_u32 v82, v84
	s_mov_b64 exec, -1
	v_subrev_u32_e32 v81, s36, v9
	v_cmp_gt_u32_e32 vcc, 0x1000000, v81
	v_bfe_u32 v82, v81, 16, 8
	v_lshl_add_u32 v82, v82, 2, v85
	s_mov_b64 exec, vcc
	ds_add_u32 v82, v84
	s_mov_b64 exec, -1
	v_subrev_u32_e32 v81, s36, v10
	v_cmp_gt_u32_e32 vcc, 0x1000000, v81
	v_bfe_u32 v82, v81, 16, 8
	v_lshl_add_u32 v82, v82, 2, v85
	s_mov_b64 exec, vcc
	ds_add_u32 v82, v84
	s_mov_b64 exec, -1
	v_subrev_u32_e32 v81, s36, v11
	v_cmp_gt_u32_e32 vcc, 0x1000000, v81
	v_bfe_u32 v82, v81, 16, 8
	v_lshl_add_u32 v82, v82, 2, v85
	s_mov_b64 exec, vcc
	ds_add_u32 v82, v84
	s_mov_b64 exec, -1
	v_subrev_u32_e32 v81, s36, v12
	v_cmp_gt_u32_e32 vcc, 0x1000000, v81
	v_bfe_u32 v82, v81, 16, 8
	v_lshl_add_u32 v82, v82, 2, v85
	s_mov_b64 exec, vcc
	ds_add_u32 v82, v84
	s_mov_b64 exec, -1
	v_subrev_u32_e32 v81, s36, v13
	v_cmp_gt_u32_e32 vcc, 0x1000000, v81
	v_bfe_u32 v82, v81, 16, 8
	v_lshl_add_u32 v82, v82, 2, v85
	s_mov_b64 exec, vcc
	ds_add_u32 v82, v84
	s_mov_b64 exec, -1
	v_subrev_u32_e32 v81, s36, v14
	v_cmp_gt_u32_e32 vcc, 0x1000000, v81
	v_bfe_u32 v82, v81, 16, 8
	v_lshl_add_u32 v82, v82, 2, v85
	s_mov_b64 exec, vcc
	ds_add_u32 v82, v84
	s_mov_b64 exec, -1
	v_subrev_u32_e32 v81, s36, v15
	v_cmp_gt_u32_e32 vcc, 0x1000000, v81
	v_bfe_u32 v82, v81, 16, 8
	v_lshl_add_u32 v82, v82, 2, v85
	s_mov_b64 exec, vcc
	ds_add_u32 v82, v84
	s_mov_b64 exec, -1
	s_cmp_lt_i32 s38, 16
	s_cbranch_scc1 .Lsel_p2_done
	v_subrev_u32_e32 v81, s36, v16
	v_cmp_gt_u32_e32 vcc, 0x1000000, v81
	v_bfe_u32 v82, v81, 16, 8
	v_lshl_add_u32 v82, v82, 2, v85
	s_mov_b64 exec, vcc
	ds_add_u32 v82, v84
	s_mov_b64 exec, -1
	v_subrev_u32_e32 v81, s36, v17
	v_cmp_gt_u32_e32 vcc, 0x1000000, v81
	v_bfe_u32 v82, v81, 16, 8
	v_lshl_add_u32 v82, v82, 2, v85
	s_mov_b64 exec, vcc
	ds_add_u32 v82, v84
	s_mov_b64 exec, -1
	v_subrev_u32_e32 v81, s36, v18
	v_cmp_gt_u32_e32 vcc, 0x1000000, v81
	v_bfe_u32 v82, v81, 16, 8
	v_lshl_add_u32 v82, v82, 2, v85
	s_mov_b64 exec, vcc
	ds_add_u32 v82, v84
	s_mov_b64 exec, -1
	v_subrev_u32_e32 v81, s36, v19
	v_cmp_gt_u32_e32 vcc, 0x1000000, v81
	v_bfe_u32 v82, v81, 16, 8
	v_lshl_add_u32 v82, v82, 2, v85
	s_mov_b64 exec, vcc
	ds_add_u32 v82, v84
	s_mov_b64 exec, -1
	v_subrev_u32_e32 v81, s36, v20
	v_cmp_gt_u32_e32 vcc, 0x1000000, v81
	v_bfe_u32 v82, v81, 16, 8
	v_lshl_add_u32 v82, v82, 2, v85
	s_mov_b64 exec, vcc
	ds_add_u32 v82, v84
	s_mov_b64 exec, -1
	v_subrev_u32_e32 v81, s36, v21
	v_cmp_gt_u32_e32 vcc, 0x1000000, v81
	v_bfe_u32 v82, v81, 16, 8
	v_lshl_add_u32 v82, v82, 2, v85
	s_mov_b64 exec, vcc
	ds_add_u32 v82, v84
	s_mov_b64 exec, -1
	v_subrev_u32_e32 v81, s36, v22
	v_cmp_gt_u32_e32 vcc, 0x1000000, v81
	v_bfe_u32 v82, v81, 16, 8
	v_lshl_add_u32 v82, v82, 2, v85
	s_mov_b64 exec, vcc
	ds_add_u32 v82, v84
	s_mov_b64 exec, -1
	v_subrev_u32_e32 v81, s36, v23
	v_cmp_gt_u32_e32 vcc, 0x1000000, v81
	v_bfe_u32 v82, v81, 16, 8
	v_lshl_add_u32 v82, v82, 2, v85
	s_mov_b64 exec, vcc
	ds_add_u32 v82, v84
	s_mov_b64 exec, -1
	s_cmp_lt_i32 s38, 24
	s_cbranch_scc1 .Lsel_p2_done
	v_subrev_u32_e32 v81, s36, v24
	v_cmp_gt_u32_e32 vcc, 0x1000000, v81
	v_bfe_u32 v82, v81, 16, 8
	v_lshl_add_u32 v82, v82, 2, v85
	s_mov_b64 exec, vcc
	ds_add_u32 v82, v84
	s_mov_b64 exec, -1
	v_subrev_u32_e32 v81, s36, v25
	v_cmp_gt_u32_e32 vcc, 0x1000000, v81
	v_bfe_u32 v82, v81, 16, 8
	v_lshl_add_u32 v82, v82, 2, v85
	s_mov_b64 exec, vcc
	ds_add_u32 v82, v84
	s_mov_b64 exec, -1
	v_subrev_u32_e32 v81, s36, v26
	v_cmp_gt_u32_e32 vcc, 0x1000000, v81
	v_bfe_u32 v82, v81, 16, 8
	v_lshl_add_u32 v82, v82, 2, v85
	s_mov_b64 exec, vcc
	ds_add_u32 v82, v84
	s_mov_b64 exec, -1
	v_subrev_u32_e32 v81, s36, v27
	v_cmp_gt_u32_e32 vcc, 0x1000000, v81
	v_bfe_u32 v82, v81, 16, 8
	v_lshl_add_u32 v82, v82, 2, v85
	s_mov_b64 exec, vcc
	ds_add_u32 v82, v84
	s_mov_b64 exec, -1
	v_subrev_u32_e32 v81, s36, v28
	v_cmp_gt_u32_e32 vcc, 0x1000000, v81
	v_bfe_u32 v82, v81, 16, 8
	v_lshl_add_u32 v82, v82, 2, v85
	s_mov_b64 exec, vcc
	ds_add_u32 v82, v84
	s_mov_b64 exec, -1
	v_subrev_u32_e32 v81, s36, v29
	v_cmp_gt_u32_e32 vcc, 0x1000000, v81
	v_bfe_u32 v82, v81, 16, 8
	v_lshl_add_u32 v82, v82, 2, v85
	s_mov_b64 exec, vcc
	ds_add_u32 v82, v84
	s_mov_b64 exec, -1
	v_subrev_u32_e32 v81, s36, v30
	v_cmp_gt_u32_e32 vcc, 0x1000000, v81
	v_bfe_u32 v82, v81, 16, 8
	v_lshl_add_u32 v82, v82, 2, v85
	s_mov_b64 exec, vcc
	ds_add_u32 v82, v84
	s_mov_b64 exec, -1
	v_subrev_u32_e32 v81, s36, v31
	v_cmp_gt_u32_e32 vcc, 0x1000000, v81
	v_bfe_u32 v82, v81, 16, 8
	v_lshl_add_u32 v82, v82, 2, v85
	s_mov_b64 exec, vcc
	ds_add_u32 v82, v84
	s_mov_b64 exec, -1
	s_cmp_lt_i32 s38, 32
	s_cbranch_scc1 .Lsel_p2_done
	v_subrev_u32_e32 v81, s36, v40
	v_cmp_gt_u32_e32 vcc, 0x1000000, v81
	v_bfe_u32 v82, v81, 16, 8
	v_lshl_add_u32 v82, v82, 2, v85
	s_mov_b64 exec, vcc
	ds_add_u32 v82, v84
	s_mov_b64 exec, -1
	v_subrev_u32_e32 v81, s36, v41
	v_cmp_gt_u32_e32 vcc, 0x1000000, v81
	v_bfe_u32 v82, v81, 16, 8
	v_lshl_add_u32 v82, v82, 2, v85
	s_mov_b64 exec, vcc
	ds_add_u32 v82, v84
	s_mov_b64 exec, -1
	v_subrev_u32_e32 v81, s36, v42
	v_cmp_gt_u32_e32 vcc, 0x1000000, v81
	v_bfe_u32 v82, v81, 16, 8
	v_lshl_add_u32 v82, v82, 2, v85
	s_mov_b64 exec, vcc
	ds_add_u32 v82, v84
	s_mov_b64 exec, -1
	v_subrev_u32_e32 v81, s36, v43
	v_cmp_gt_u32_e32 vcc, 0x1000000, v81
	v_bfe_u32 v82, v81, 16, 8
	v_lshl_add_u32 v82, v82, 2, v85
	s_mov_b64 exec, vcc
	ds_add_u32 v82, v84
	s_mov_b64 exec, -1
	v_subrev_u32_e32 v81, s36, v44
	v_cmp_gt_u32_e32 vcc, 0x1000000, v81
	v_bfe_u32 v82, v81, 16, 8
	v_lshl_add_u32 v82, v82, 2, v85
	s_mov_b64 exec, vcc
	ds_add_u32 v82, v84
	s_mov_b64 exec, -1
	v_subrev_u32_e32 v81, s36, v45
	v_cmp_gt_u32_e32 vcc, 0x1000000, v81
	v_bfe_u32 v82, v81, 16, 8
	v_lshl_add_u32 v82, v82, 2, v85
	s_mov_b64 exec, vcc
	ds_add_u32 v82, v84
	s_mov_b64 exec, -1
	v_subrev_u32_e32 v81, s36, v46
	v_cmp_gt_u32_e32 vcc, 0x1000000, v81
	v_bfe_u32 v82, v81, 16, 8
	v_lshl_add_u32 v82, v82, 2, v85
	s_mov_b64 exec, vcc
	ds_add_u32 v82, v84
	s_mov_b64 exec, -1
	v_subrev_u32_e32 v81, s36, v47
	v_cmp_gt_u32_e32 vcc, 0x1000000, v81
	v_bfe_u32 v82, v81, 16, 8
	v_lshl_add_u32 v82, v82, 2, v85
	s_mov_b64 exec, vcc
	ds_add_u32 v82, v84
	s_mov_b64 exec, -1
	s_cmp_lt_i32 s38, 40
	s_cbranch_scc1 .Lsel_p2_done
	v_subrev_u32_e32 v81, s36, v48
	v_cmp_gt_u32_e32 vcc, 0x1000000, v81
	v_bfe_u32 v82, v81, 16, 8
	v_lshl_add_u32 v82, v82, 2, v85
	s_mov_b64 exec, vcc
	ds_add_u32 v82, v84
	s_mov_b64 exec, -1
	v_subrev_u32_e32 v81, s36, v49
	v_cmp_gt_u32_e32 vcc, 0x1000000, v81
	v_bfe_u32 v82, v81, 16, 8
	v_lshl_add_u32 v82, v82, 2, v85
	s_mov_b64 exec, vcc
	ds_add_u32 v82, v84
	s_mov_b64 exec, -1
	v_subrev_u32_e32 v81, s36, v50
	v_cmp_gt_u32_e32 vcc, 0x1000000, v81
	v_bfe_u32 v82, v81, 16, 8
	v_lshl_add_u32 v82, v82, 2, v85
	s_mov_b64 exec, vcc
	ds_add_u32 v82, v84
	s_mov_b64 exec, -1
	v_subrev_u32_e32 v81, s36, v51
	v_cmp_gt_u32_e32 vcc, 0x1000000, v81
	v_bfe_u32 v82, v81, 16, 8
	v_lshl_add_u32 v82, v82, 2, v85
	s_mov_b64 exec, vcc
	ds_add_u32 v82, v84
	s_mov_b64 exec, -1
	v_subrev_u32_e32 v81, s36, v52
	v_cmp_gt_u32_e32 vcc, 0x1000000, v81
	v_bfe_u32 v82, v81, 16, 8
	v_lshl_add_u32 v82, v82, 2, v85
	s_mov_b64 exec, vcc
	ds_add_u32 v82, v84
	s_mov_b64 exec, -1
	v_subrev_u32_e32 v81, s36, v53
	v_cmp_gt_u32_e32 vcc, 0x1000000, v81
	v_bfe_u32 v82, v81, 16, 8
	v_lshl_add_u32 v82, v82, 2, v85
	s_mov_b64 exec, vcc
	ds_add_u32 v82, v84
	s_mov_b64 exec, -1
	v_subrev_u32_e32 v81, s36, v54
	v_cmp_gt_u32_e32 vcc, 0x1000000, v81
	v_bfe_u32 v82, v81, 16, 8
	v_lshl_add_u32 v82, v82, 2, v85
	s_mov_b64 exec, vcc
	ds_add_u32 v82, v84
	s_mov_b64 exec, -1
	v_subrev_u32_e32 v81, s36, v55
	v_cmp_gt_u32_e32 vcc, 0x1000000, v81
	v_bfe_u32 v82, v81, 16, 8
	v_lshl_add_u32 v82, v82, 2, v85
	s_mov_b64 exec, vcc
	ds_add_u32 v82, v84
	s_mov_b64 exec, -1
	s_cmp_lt_i32 s38, 48
	s_cbranch_scc1 .Lsel_p2_done
	v_subrev_u32_e32 v81, s36, v56
	v_cmp_gt_u32_e32 vcc, 0x1000000, v81
	v_bfe_u32 v82, v81, 16, 8
	v_lshl_add_u32 v82, v82, 2, v85
	s_mov_b64 exec, vcc
	ds_add_u32 v82, v84
	s_mov_b64 exec, -1
	v_subrev_u32_e32 v81, s36, v57
	v_cmp_gt_u32_e32 vcc, 0x1000000, v81
	v_bfe_u32 v82, v81, 16, 8
	v_lshl_add_u32 v82, v82, 2, v85
	s_mov_b64 exec, vcc
	ds_add_u32 v82, v84
	s_mov_b64 exec, -1
	v_subrev_u32_e32 v81, s36, v58
	v_cmp_gt_u32_e32 vcc, 0x1000000, v81
	v_bfe_u32 v82, v81, 16, 8
	v_lshl_add_u32 v82, v82, 2, v85
	s_mov_b64 exec, vcc
	ds_add_u32 v82, v84
	s_mov_b64 exec, -1
	v_subrev_u32_e32 v81, s36, v59
	v_cmp_gt_u32_e32 vcc, 0x1000000, v81
	v_bfe_u32 v82, v81, 16, 8
	v_lshl_add_u32 v82, v82, 2, v85
	s_mov_b64 exec, vcc
	ds_add_u32 v82, v84
	s_mov_b64 exec, -1
	v_subrev_u32_e32 v81, s36, v60
	v_cmp_gt_u32_e32 vcc, 0x1000000, v81
	v_bfe_u32 v82, v81, 16, 8
	v_lshl_add_u32 v82, v82, 2, v85
	s_mov_b64 exec, vcc
	ds_add_u32 v82, v84
	s_mov_b64 exec, -1
	v_subrev_u32_e32 v81, s36, v61
	v_cmp_gt_u32_e32 vcc, 0x1000000, v81
	v_bfe_u32 v82, v81, 16, 8
	v_lshl_add_u32 v82, v82, 2, v85
	s_mov_b64 exec, vcc
	ds_add_u32 v82, v84
	s_mov_b64 exec, -1
	v_subrev_u32_e32 v81, s36, v62
	v_cmp_gt_u32_e32 vcc, 0x1000000, v81
	v_bfe_u32 v82, v81, 16, 8
	v_lshl_add_u32 v82, v82, 2, v85
	s_mov_b64 exec, vcc
	ds_add_u32 v82, v84
	s_mov_b64 exec, -1
	v_subrev_u32_e32 v81, s36, v63
	v_cmp_gt_u32_e32 vcc, 0x1000000, v81
	v_bfe_u32 v82, v81, 16, 8
	v_lshl_add_u32 v82, v82, 2, v85
	s_mov_b64 exec, vcc
	ds_add_u32 v82, v84
	s_mov_b64 exec, -1
	s_cmp_lt_i32 s38, 56
	s_cbranch_scc1 .Lsel_p2_done
	v_subrev_u32_e32 v81, s36, v64
	v_cmp_gt_u32_e32 vcc, 0x1000000, v81
	v_bfe_u32 v82, v81, 16, 8
	v_lshl_add_u32 v82, v82, 2, v85
	s_mov_b64 exec, vcc
	ds_add_u32 v82, v84
	s_mov_b64 exec, -1
	v_subrev_u32_e32 v81, s36, v65
	v_cmp_gt_u32_e32 vcc, 0x1000000, v81
	v_bfe_u32 v82, v81, 16, 8
	v_lshl_add_u32 v82, v82, 2, v85
	s_mov_b64 exec, vcc
	ds_add_u32 v82, v84
	s_mov_b64 exec, -1
	v_subrev_u32_e32 v81, s36, v66
	v_cmp_gt_u32_e32 vcc, 0x1000000, v81
	v_bfe_u32 v82, v81, 16, 8
	v_lshl_add_u32 v82, v82, 2, v85
	s_mov_b64 exec, vcc
	ds_add_u32 v82, v84
	s_mov_b64 exec, -1
	v_subrev_u32_e32 v81, s36, v67
	v_cmp_gt_u32_e32 vcc, 0x1000000, v81
	v_bfe_u32 v82, v81, 16, 8
	v_lshl_add_u32 v82, v82, 2, v85
	s_mov_b64 exec, vcc
	ds_add_u32 v82, v84
	s_mov_b64 exec, -1
	v_subrev_u32_e32 v81, s36, v68
	v_cmp_gt_u32_e32 vcc, 0x1000000, v81
	v_bfe_u32 v82, v81, 16, 8
	v_lshl_add_u32 v82, v82, 2, v85
	s_mov_b64 exec, vcc
	ds_add_u32 v82, v84
	s_mov_b64 exec, -1
	v_subrev_u32_e32 v81, s36, v69
	v_cmp_gt_u32_e32 vcc, 0x1000000, v81
	v_bfe_u32 v82, v81, 16, 8
	v_lshl_add_u32 v82, v82, 2, v85
	s_mov_b64 exec, vcc
	ds_add_u32 v82, v84
	s_mov_b64 exec, -1
	v_subrev_u32_e32 v81, s36, v70
	v_cmp_gt_u32_e32 vcc, 0x1000000, v81
	v_bfe_u32 v82, v81, 16, 8
	v_lshl_add_u32 v82, v82, 2, v85
	s_mov_b64 exec, vcc
	ds_add_u32 v82, v84
	s_mov_b64 exec, -1
	v_subrev_u32_e32 v81, s36, v71
	v_cmp_gt_u32_e32 vcc, 0x1000000, v81
	v_bfe_u32 v82, v81, 16, 8
	v_lshl_add_u32 v82, v82, 2, v85
	s_mov_b64 exec, vcc
	ds_add_u32 v82, v84
	s_mov_b64 exec, -1
.Lsel_p2_done:
	s_waitcnt lgkmcnt(0)
	ds_read_b128 v[88:91], v87
	s_waitcnt lgkmcnt(0)
	ds_write_b128 v86, v[100:103]
	v_add3_u32 v92, v88, v89, v90
	v_add_u32_e32 v92, v92, v91
	v_mov_b32_e32 v93, v92
	s_nop 1
	v_add_u32_dpp v93, v93, v93 row_shr:1 row_mask:0xf bank_mask:0xf
	s_nop 1
	v_add_u32_dpp v93, v93, v93 row_shr:2 row_mask:0xf bank_mask:0xf
	s_nop 1
	v_add_u32_dpp v93, v93, v93 row_shr:4 row_mask:0xf bank_mask:0xf
	s_nop 1
	v_add_u32_dpp v93, v93, v93 row_shr:8 row_mask:0xf bank_mask:0xf
	s_nop 1
	v_readlane_b32 s40, v93, 15
	v_readlane_b32 s41, v93, 31
	v_readlane_b32 s42, v93, 47
	s_add_i32 s41, s40, s41
	s_add_i32 s42, s41, s42
	s_mov_b32 exec_lo, 0xffff0000
	s_mov_b32 exec_hi, 0
	v_add_u32_e32 v93, s40, v93
	s_mov_b32 exec_lo, 0
	s_mov_b32 exec_hi, 0xffff
	v_add_u32_e32 v93, s41, v93
	s_mov_b32 exec_hi, 0xffff0000
	v_add_u32_e32 v93, s42, v93
	s_mov_b64 exec, -1
	v_sub_u32_e32 v94, v93, v92
	v_add_u32_e32 v95, v94, v91
	v_add_u32_e32 v96, v95, v90
	v_add_u32_e32 v97, v96, v89
	v_cmp_gt_u32_e32 vcc, s29, v94
	s_bcnt1_i32_b64 s30, vcc
	v_cmp_gt_u32_e32 vcc, s29, v95
	s_bcnt1_i32_b64 s4, vcc
	s_add_i32 s30, s30, s4
	v_cmp_gt_u32_e32 vcc, s29, v96
	s_bcnt1_i32_b64 s4, vcc
	s_add_i32 s30, s30, s4
	v_cmp_gt_u32_e32 vcc, s29, v97
	s_bcnt1_i32_b64 s4, vcc
	s_add_i32 s30, s30, s4
	s_add_i32 s30, s30, -1
	s_lshr_b32 s5, s30, 2
	s_and_b32 s6, s30, 3
	s_sub_i32 s37, 0xff, s30
	s_nop 3
	v_readlane_b32 s40, v94, s5
	v_readlane_b32 s41, v95, s5
	v_readlane_b32 s42, v96, s5
	v_readlane_b32 s43, v97, s5
	s_cmp_eq_u32 s6, 1
	s_cselect_b32 s40, s41, s40
	s_cmp_eq_u32 s6, 2
	s_cselect_b32 s40, s42, s40
	s_cmp_eq_u32 s6, 3
	s_cselect_b32 s40, s43, s40
	s_lshl_b32 s36, s34, 8
	s_or_b32 s36, s36, s37
	s_lshl_b32 s37, s36, 16
	s_or_b32 s44, s37, 0xffff
	s_add_i32 s45, s35, s40
	v_mov_b32_e32 v98, 0
	v_mov_b32_e32 v99, s45
	v_cmp_lt_u32_e32 vcc, s44, v0
	v_cmp_le_u32_e64 s[0:1], s37, v0
	s_bcnt1_i32_b64 s4, vcc
	v_mbcnt_lo_u32_b32 v72, vcc_lo, v98
	v_mbcnt_hi_u32_b32 v72, vcc_hi, v72
	v_add_u32_e32 v98, s4, v98
	v_lshlrev_b32_e32 v73, 2, v72
	s_mov_b64 exec, vcc
	global_store_dword v73, v34, s[2:3]
	s_mov_b64 exec, -1
	s_andn2_b64 s[0:1], s[0:1], vcc
	s_cbranch_scc1 .Lsel_eq0
.Lsel_eqb0:
	v_cmp_lt_u32_e32 vcc, s44, v1
	v_cmp_le_u32_e64 s[0:1], s37, v1
	s_bcnt1_i32_b64 s4, vcc
	v_mbcnt_lo_u32_b32 v72, vcc_lo, v98
	v_mbcnt_hi_u32_b32 v72, vcc_hi, v72
	v_add_u32_e32 v98, s4, v98
	v_lshlrev_b32_e32 v73, 2, v72
	s_mov_b64 exec, vcc
	global_store_dword v73, v115, s[2:3]
	s_mov_b64 exec, -1
	s_andn2_b64 s[0:1], s[0:1], vcc
	s_cbranch_scc1 .Lsel_eq1
.Lsel_eqb1:
	v_cmp_lt_u32_e32 vcc, s44, v2
	v_cmp_le_u32_e64 s[0:1], s37, v2
	s_bcnt1_i32_b64 s4, vcc
	v_mbcnt_lo_u32_b32 v72, vcc_lo, v98
	v_mbcnt_hi_u32_b32 v72, vcc_hi, v72
	v_add_u32_e32 v98, s4, v98
	v_lshlrev_b32_e32 v73, 2, v72
	s_mov_b64 exec, vcc
	global_store_dword v73, v116, s[2:3]
	s_mov_b64 exec, -1
	s_andn2_b64 s[0:1], s[0:1], vcc
	s_cbranch_scc1 .Lsel_eq2
.Lsel_eqb2:
	v_cmp_lt_u32_e32 vcc, s44, v3
	v_cmp_le_u32_e64 s[0:1], s37, v3
	s_bcnt1_i32_b64 s4, vcc
	v_mbcnt_lo_u32_b32 v72, vcc_lo, v98
	v_mbcnt_hi_u32_b32 v72, vcc_hi, v72
	v_add_u32_e32 v98, s4, v98
	v_lshlrev_b32_e32 v73, 2, v72
	s_mov_b64 exec, vcc
	global_store_dword v73, v117, s[2:3]
	s_mov_b64 exec, -1
	s_andn2_b64 s[0:1], s[0:1], vcc
	s_cbranch_scc1 .Lsel_eq3
.Lsel_eqb3:
	v_cmp_lt_u32_e32 vcc, s44, v4
	v_cmp_le_u32_e64 s[0:1], s37, v4
	s_bcnt1_i32_b64 s4, vcc
	v_mbcnt_lo_u32_b32 v72, vcc_lo, v98
	v_mbcnt_hi_u32_b32 v72, vcc_hi, v72
	v_add_u32_e32 v98, s4, v98
	v_lshlrev_b32_e32 v73, 2, v72
	s_mov_b64 exec, vcc
	global_store_dword v73, v118, s[2:3]
	s_mov_b64 exec, -1
	s_andn2_b64 s[0:1], s[0:1], vcc
	s_cbranch_scc1 .Lsel_eq4
.Lsel_eqb4:
	v_cmp_lt_u32_e32 vcc, s44, v5
	v_cmp_le_u32_e64 s[0:1], s37, v5
	s_bcnt1_i32_b64 s4, vcc
	v_mbcnt_lo_u32_b32 v72, vcc_lo, v98
	v_mbcnt_hi_u32_b32 v72, vcc_hi, v72
	v_add_u32_e32 v98, s4, v98
	v_lshlrev_b32_e32 v73, 2, v72
	s_mov_b64 exec, vcc
	global_store_dword v73, v119, s[2:3]
	s_mov_b64 exec, -1
	s_andn2_b64 s[0:1], s[0:1], vcc
	s_cbranch_scc1 .Lsel_eq5
.Lsel_eqb5:
	v_cmp_lt_u32_e32 vcc, s44, v6
	v_cmp_le_u32_e64 s[0:1], s37, v6
	s_bcnt1_i32_b64 s4, vcc
	v_mbcnt_lo_u32_b32 v72, vcc_lo, v98
	v_mbcnt_hi_u32_b32 v72, vcc_hi, v72
	v_add_u32_e32 v98, s4, v98
	v_lshlrev_b32_e32 v73, 2, v72
	s_mov_b64 exec, vcc
	global_store_dword v73, v120, s[2:3]
	s_mov_b64 exec, -1
	s_andn2_b64 s[0:1], s[0:1], vcc
	s_cbranch_scc1 .Lsel_eq6
.Lsel_eqb6:
	v_cmp_lt_u32_e32 vcc, s44, v7
	v_cmp_le_u32_e64 s[0:1], s37, v7
	s_bcnt1_i32_b64 s4, vcc
	v_mbcnt_lo_u32_b32 v72, vcc_lo, v98
	v_mbcnt_hi_u32_b32 v72, vcc_hi, v72
	v_add_u32_e32 v98, s4, v98
	v_lshlrev_b32_e32 v73, 2, v72
	s_mov_b64 exec, vcc
	global_store_dword v73, v121, s[2:3]
	s_mov_b64 exec, -1
	s_andn2_b64 s[0:1], s[0:1], vcc
	s_cbranch_scc1 .Lsel_eq7
.Lsel_eqb7:
	s_cmp_lt_i32 s38, 8
	s_cbranch_scc1 .Lsel_cp_done
	v_cmp_lt_u32_e32 vcc, s44, v8
	v_cmp_le_u32_e64 s[0:1], s37, v8
	s_bcnt1_i32_b64 s4, vcc
	v_mbcnt_lo_u32_b32 v72, vcc_lo, v98
	v_mbcnt_hi_u32_b32 v72, vcc_hi, v72
	v_add_u32_e32 v98, s4, v98
	v_lshlrev_b32_e32 v73, 2, v72
	s_mov_b64 exec, vcc
	global_store_dword v73, v122, s[2:3]
	s_mov_b64 exec, -1
	s_andn2_b64 s[0:1], s[0:1], vcc
	s_cbranch_scc1 .Lsel_eq8
.Lsel_eqb8:
	v_cmp_lt_u32_e32 vcc, s44, v9
	v_cmp_le_u32_e64 s[0:1], s37, v9
	s_bcnt1_i32_b64 s4, vcc
	v_mbcnt_lo_u32_b32 v72, vcc_lo, v98
	v_mbcnt_hi_u32_b32 v72, vcc_hi, v72
	v_add_u32_e32 v98, s4, v98
	v_lshlrev_b32_e32 v73, 2, v72
	s_mov_b64 exec, vcc
	global_store_dword v73, v123, s[2:3]
	s_mov_b64 exec, -1
	s_andn2_b64 s[0:1], s[0:1], vcc
	s_cbranch_scc1 .Lsel_eq9
.Lsel_eqb9:
	v_cmp_lt_u32_e32 vcc, s44, v10
	v_cmp_le_u32_e64 s[0:1], s37, v10
	s_bcnt1_i32_b64 s4, vcc
	v_mbcnt_lo_u32_b32 v72, vcc_lo, v98
	v_mbcnt_hi_u32_b32 v72, vcc_hi, v72
	v_add_u32_e32 v98, s4, v98
	v_lshlrev_b32_e32 v73, 2, v72
	s_mov_b64 exec, vcc
	global_store_dword v73, v124, s[2:3]
	s_mov_b64 exec, -1
	s_andn2_b64 s[0:1], s[0:1], vcc
	s_cbranch_scc1 .Lsel_eq10
.Lsel_eqb10:
	v_cmp_lt_u32_e32 vcc, s44, v11
	v_cmp_le_u32_e64 s[0:1], s37, v11
	s_bcnt1_i32_b64 s4, vcc
	v_mbcnt_lo_u32_b32 v72, vcc_lo, v98
	v_mbcnt_hi_u32_b32 v72, vcc_hi, v72
	v_add_u32_e32 v98, s4, v98
	v_lshlrev_b32_e32 v73, 2, v72
	s_mov_b64 exec, vcc
	global_store_dword v73, v125, s[2:3]
	s_mov_b64 exec, -1
	s_andn2_b64 s[0:1], s[0:1], vcc
	s_cbranch_scc1 .Lsel_eq11
.Lsel_eqb11:
	v_cmp_lt_u32_e32 vcc, s44, v12
	v_cmp_le_u32_e64 s[0:1], s37, v12
	s_bcnt1_i32_b64 s4, vcc
	v_mbcnt_lo_u32_b32 v72, vcc_lo, v98
	v_mbcnt_hi_u32_b32 v72, vcc_hi, v72
	v_add_u32_e32 v98, s4, v98
	v_lshlrev_b32_e32 v73, 2, v72
	s_mov_b64 exec, vcc
	global_store_dword v73, v126, s[2:3]
	s_mov_b64 exec, -1
	s_andn2_b64 s[0:1], s[0:1], vcc
	s_cbranch_scc1 .Lsel_eq12
.Lsel_eqb12:
	v_cmp_lt_u32_e32 vcc, s44, v13
	v_cmp_le_u32_e64 s[0:1], s37, v13
	s_bcnt1_i32_b64 s4, vcc
	v_mbcnt_lo_u32_b32 v72, vcc_lo, v98
	v_mbcnt_hi_u32_b32 v72, vcc_hi, v72
	v_add_u32_e32 v98, s4, v98
	v_lshlrev_b32_e32 v73, 2, v72
	s_mov_b64 exec, vcc
	global_store_dword v73, v127, s[2:3]
	s_mov_b64 exec, -1
	s_andn2_b64 s[0:1], s[0:1], vcc
	s_cbranch_scc1 .Lsel_eq13
.Lsel_eqb13:
	v_cmp_lt_u32_e32 vcc, s44, v14
	v_cmp_le_u32_e64 s[0:1], s37, v14
	s_bcnt1_i32_b64 s4, vcc
	v_mbcnt_lo_u32_b32 v72, vcc_lo, v98
	v_mbcnt_hi_u32_b32 v72, vcc_hi, v72
	v_add_u32_e32 v98, s4, v98
	v_lshlrev_b32_e32 v73, 2, v72
	s_mov_b64 exec, vcc
	global_store_dword v73, v128, s[2:3]
	s_mov_b64 exec, -1
	s_andn2_b64 s[0:1], s[0:1], vcc
	s_cbranch_scc1 .Lsel_eq14
.Lsel_eqb14:
	v_cmp_lt_u32_e32 vcc, s44, v15
	v_cmp_le_u32_e64 s[0:1], s37, v15
	s_bcnt1_i32_b64 s4, vcc
	v_mbcnt_lo_u32_b32 v72, vcc_lo, v98
	v_mbcnt_hi_u32_b32 v72, vcc_hi, v72
	v_add_u32_e32 v98, s4, v98
	v_lshlrev_b32_e32 v73, 2, v72
	s_mov_b64 exec, vcc
	global_store_dword v73, v129, s[2:3]
	s_mov_b64 exec, -1
	s_andn2_b64 s[0:1], s[0:1], vcc
	s_cbranch_scc1 .Lsel_eq15
.Lsel_eqb15:
	s_cmp_lt_i32 s38, 16
	s_cbranch_scc1 .Lsel_cp_done
	v_cmp_lt_u32_e32 vcc, s44, v16
	v_cmp_le_u32_e64 s[0:1], s37, v16
	s_bcnt1_i32_b64 s4, vcc
	v_mbcnt_lo_u32_b32 v72, vcc_lo, v98
	v_mbcnt_hi_u32_b32 v72, vcc_hi, v72
	v_add_u32_e32 v98, s4, v98
	v_lshlrev_b32_e32 v73, 2, v72
	s_mov_b64 exec, vcc
	global_store_dword v73, v130, s[2:3]
	s_mov_b64 exec, -1
	s_andn2_b64 s[0:1], s[0:1], vcc
	s_cbranch_scc1 .Lsel_eq16
.Lsel_eqb16:
	v_cmp_lt_u32_e32 vcc, s44, v17
	v_cmp_le_u32_e64 s[0:1], s37, v17
	s_bcnt1_i32_b64 s4, vcc
	v_mbcnt_lo_u32_b32 v72, vcc_lo, v98
	v_mbcnt_hi_u32_b32 v72, vcc_hi, v72
	v_add_u32_e32 v98, s4, v98
	v_lshlrev_b32_e32 v73, 2, v72
	s_mov_b64 exec, vcc
	global_store_dword v73, v131, s[2:3]
	s_mov_b64 exec, -1
	s_andn2_b64 s[0:1], s[0:1], vcc
	s_cbranch_scc1 .Lsel_eq17
.Lsel_eqb17:
	v_cmp_lt_u32_e32 vcc, s44, v18
	v_cmp_le_u32_e64 s[0:1], s37, v18
	s_bcnt1_i32_b64 s4, vcc
	v_mbcnt_lo_u32_b32 v72, vcc_lo, v98
	v_mbcnt_hi_u32_b32 v72, vcc_hi, v72
	v_add_u32_e32 v98, s4, v98
	v_lshlrev_b32_e32 v73, 2, v72
	s_mov_b64 exec, vcc
	global_store_dword v73, v132, s[2:3]
	s_mov_b64 exec, -1
	s_andn2_b64 s[0:1], s[0:1], vcc
	s_cbranch_scc1 .Lsel_eq18
.Lsel_eqb18:
	v_cmp_lt_u32_e32 vcc, s44, v19
	v_cmp_le_u32_e64 s[0:1], s37, v19
	s_bcnt1_i32_b64 s4, vcc
	v_mbcnt_lo_u32_b32 v72, vcc_lo, v98
	v_mbcnt_hi_u32_b32 v72, vcc_hi, v72
	v_add_u32_e32 v98, s4, v98
	v_lshlrev_b32_e32 v73, 2, v72
	s_mov_b64 exec, vcc
	global_store_dword v73, v133, s[2:3]
	s_mov_b64 exec, -1
	s_andn2_b64 s[0:1], s[0:1], vcc
	s_cbranch_scc1 .Lsel_eq19
.Lsel_eqb19:
	v_cmp_lt_u32_e32 vcc, s44, v20
	v_cmp_le_u32_e64 s[0:1], s37, v20
	s_bcnt1_i32_b64 s4, vcc
	v_mbcnt_lo_u32_b32 v72, vcc_lo, v98
	v_mbcnt_hi_u32_b32 v72, vcc_hi, v72
	v_add_u32_e32 v98, s4, v98
	v_lshlrev_b32_e32 v73, 2, v72
	s_mov_b64 exec, vcc
	global_store_dword v73, v134, s[2:3]
	s_mov_b64 exec, -1
	s_andn2_b64 s[0:1], s[0:1], vcc
	s_cbranch_scc1 .Lsel_eq20
.Lsel_eqb20:
	v_cmp_lt_u32_e32 vcc, s44, v21
	v_cmp_le_u32_e64 s[0:1], s37, v21
	s_bcnt1_i32_b64 s4, vcc
	v_mbcnt_lo_u32_b32 v72, vcc_lo, v98
	v_mbcnt_hi_u32_b32 v72, vcc_hi, v72
	v_add_u32_e32 v98, s4, v98
	v_lshlrev_b32_e32 v73, 2, v72
	s_mov_b64 exec, vcc
	global_store_dword v73, v135, s[2:3]
	s_mov_b64 exec, -1
	s_andn2_b64 s[0:1], s[0:1], vcc
	s_cbranch_scc1 .Lsel_eq21
.Lsel_eqb21:
	v_cmp_lt_u32_e32 vcc, s44, v22
	v_cmp_le_u32_e64 s[0:1], s37, v22
	s_bcnt1_i32_b64 s4, vcc
	v_mbcnt_lo_u32_b32 v72, vcc_lo, v98
	v_mbcnt_hi_u32_b32 v72, vcc_hi, v72
	v_add_u32_e32 v98, s4, v98
	v_lshlrev_b32_e32 v73, 2, v72
	s_mov_b64 exec, vcc
	global_store_dword v73, v144, s[2:3]
	s_mov_b64 exec, -1
	s_andn2_b64 s[0:1], s[0:1], vcc
	s_cbranch_scc1 .Lsel_eq22
.Lsel_eqb22:
	v_cmp_lt_u32_e32 vcc, s44, v23
	v_cmp_le_u32_e64 s[0:1], s37, v23
	s_bcnt1_i32_b64 s4, vcc
	v_mbcnt_lo_u32_b32 v72, vcc_lo, v98
	v_mbcnt_hi_u32_b32 v72, vcc_hi, v72
	v_add_u32_e32 v98, s4, v98
	v_lshlrev_b32_e32 v73, 2, v72
	s_mov_b64 exec, vcc
	global_store_dword v73, v145, s[2:3]
	s_mov_b64 exec, -1
	s_andn2_b64 s[0:1], s[0:1], vcc
	s_cbranch_scc1 .Lsel_eq23
.Lsel_eqb23:
	s_cmp_lt_i32 s38, 24
	s_cbranch_scc1 .Lsel_cp_done
	v_cmp_lt_u32_e32 vcc, s44, v24
	v_cmp_le_u32_e64 s[0:1], s37, v24
	s_bcnt1_i32_b64 s4, vcc
	v_mbcnt_lo_u32_b32 v72, vcc_lo, v98
	v_mbcnt_hi_u32_b32 v72, vcc_hi, v72
	v_add_u32_e32 v98, s4, v98
	v_lshlrev_b32_e32 v73, 2, v72
	s_mov_b64 exec, vcc
	global_store_dword v73, v146, s[2:3]
	s_mov_b64 exec, -1
	s_andn2_b64 s[0:1], s[0:1], vcc
	s_cbranch_scc1 .Lsel_eq24
.Lsel_eqb24:
	v_cmp_lt_u32_e32 vcc, s44, v25
	v_cmp_le_u32_e64 s[0:1], s37, v25
	s_bcnt1_i32_b64 s4, vcc
	v_mbcnt_lo_u32_b32 v72, vcc_lo, v98
	v_mbcnt_hi_u32_b32 v72, vcc_hi, v72
	v_add_u32_e32 v98, s4, v98
	v_lshlrev_b32_e32 v73, 2, v72
	s_mov_b64 exec, vcc
	global_store_dword v73, v147, s[2:3]
	s_mov_b64 exec, -1
	s_andn2_b64 s[0:1], s[0:1], vcc
	s_cbranch_scc1 .Lsel_eq25
.Lsel_eqb25:
	v_cmp_lt_u32_e32 vcc, s44, v26
	v_cmp_le_u32_e64 s[0:1], s37, v26
	s_bcnt1_i32_b64 s4, vcc
	v_mbcnt_lo_u32_b32 v72, vcc_lo, v98
	v_mbcnt_hi_u32_b32 v72, vcc_hi, v72
	v_add_u32_e32 v98, s4, v98
	v_lshlrev_b32_e32 v73, 2, v72
	s_mov_b64 exec, vcc
	global_store_dword v73, v148, s[2:3]
	s_mov_b64 exec, -1
	s_andn2_b64 s[0:1], s[0:1], vcc
	s_cbranch_scc1 .Lsel_eq26
.Lsel_eqb26:
	v_cmp_lt_u32_e32 vcc, s44, v27
	v_cmp_le_u32_e64 s[0:1], s37, v27
	s_bcnt1_i32_b64 s4, vcc
	v_mbcnt_lo_u32_b32 v72, vcc_lo, v98
	v_mbcnt_hi_u32_b32 v72, vcc_hi, v72
	v_add_u32_e32 v98, s4, v98
	v_lshlrev_b32_e32 v73, 2, v72
	s_mov_b64 exec, vcc
	global_store_dword v73, v149, s[2:3]
	s_mov_b64 exec, -1
	s_andn2_b64 s[0:1], s[0:1], vcc
	s_cbranch_scc1 .Lsel_eq27
.Lsel_eqb27:
	v_cmp_lt_u32_e32 vcc, s44, v28
	v_cmp_le_u32_e64 s[0:1], s37, v28
	s_bcnt1_i32_b64 s4, vcc
	v_mbcnt_lo_u32_b32 v72, vcc_lo, v98
	v_mbcnt_hi_u32_b32 v72, vcc_hi, v72
	v_add_u32_e32 v98, s4, v98
	v_lshlrev_b32_e32 v73, 2, v72
	s_mov_b64 exec, vcc
	global_store_dword v73, v150, s[2:3]
	s_mov_b64 exec, -1
	s_andn2_b64 s[0:1], s[0:1], vcc
	s_cbranch_scc1 .Lsel_eq28
.Lsel_eqb28:
	v_cmp_lt_u32_e32 vcc, s44, v29
	v_cmp_le_u32_e64 s[0:1], s37, v29
	s_bcnt1_i32_b64 s4, vcc
	v_mbcnt_lo_u32_b32 v72, vcc_lo, v98
	v_mbcnt_hi_u32_b32 v72, vcc_hi, v72
	v_add_u32_e32 v98, s4, v98
	v_lshlrev_b32_e32 v73, 2, v72
	s_mov_b64 exec, vcc
	global_store_dword v73, v151, s[2:3]
	s_mov_b64 exec, -1
	s_andn2_b64 s[0:1], s[0:1], vcc
	s_cbranch_scc1 .Lsel_eq29
.Lsel_eqb29:
	v_cmp_lt_u32_e32 vcc, s44, v30
	v_cmp_le_u32_e64 s[0:1], s37, v30
	s_bcnt1_i32_b64 s4, vcc
	v_mbcnt_lo_u32_b32 v72, vcc_lo, v98
	v_mbcnt_hi_u32_b32 v72, vcc_hi, v72
	v_add_u32_e32 v98, s4, v98
	v_lshlrev_b32_e32 v73, 2, v72
	s_mov_b64 exec, vcc
	global_store_dword v73, v152, s[2:3]
	s_mov_b64 exec, -1
	s_andn2_b64 s[0:1], s[0:1], vcc
	s_cbranch_scc1 .Lsel_eq30
.Lsel_eqb30:
	v_cmp_lt_u32_e32 vcc, s44, v31
	v_cmp_le_u32_e64 s[0:1], s37, v31
	s_bcnt1_i32_b64 s4, vcc
	v_mbcnt_lo_u32_b32 v72, vcc_lo, v98
	v_mbcnt_hi_u32_b32 v72, vcc_hi, v72
	v_add_u32_e32 v98, s4, v98
	v_lshlrev_b32_e32 v73, 2, v72
	s_mov_b64 exec, vcc
	global_store_dword v73, v153, s[2:3]
	s_mov_b64 exec, -1
	s_andn2_b64 s[0:1], s[0:1], vcc
	s_cbranch_scc1 .Lsel_eq31
.Lsel_eqb31:
	s_cmp_lt_i32 s38, 32
	s_cbranch_scc1 .Lsel_cp_done
	v_cmp_lt_u32_e32 vcc, s44, v40
	v_cmp_le_u32_e64 s[0:1], s37, v40
	s_bcnt1_i32_b64 s4, vcc
	v_mbcnt_lo_u32_b32 v72, vcc_lo, v98
	v_mbcnt_hi_u32_b32 v72, vcc_hi, v72
	v_add_u32_e32 v98, s4, v98
	v_lshlrev_b32_e32 v73, 2, v72
	s_mov_b64 exec, vcc
	global_store_dword v73, v154, s[2:3]
	s_mov_b64 exec, -1
	s_andn2_b64 s[0:1], s[0:1], vcc
	s_cbranch_scc1 .Lsel_eq32
.Lsel_eqb32:
	v_cmp_lt_u32_e32 vcc, s44, v41
	v_cmp_le_u32_e64 s[0:1], s37, v41
	s_bcnt1_i32_b64 s4, vcc
	v_mbcnt_lo_u32_b32 v72, vcc_lo, v98
	v_mbcnt_hi_u32_b32 v72, vcc_hi, v72
	v_add_u32_e32 v98, s4, v98
	v_lshlrev_b32_e32 v73, 2, v72
	s_mov_b64 exec, vcc
	global_store_dword v73, v155, s[2:3]
	s_mov_b64 exec, -1
	s_andn2_b64 s[0:1], s[0:1], vcc
	s_cbranch_scc1 .Lsel_eq33
.Lsel_eqb33:
	v_cmp_lt_u32_e32 vcc, s44, v42
	v_cmp_le_u32_e64 s[0:1], s37, v42
	s_bcnt1_i32_b64 s4, vcc
	v_mbcnt_lo_u32_b32 v72, vcc_lo, v98
	v_mbcnt_hi_u32_b32 v72, vcc_hi, v72
	v_add_u32_e32 v98, s4, v98
	v_lshlrev_b32_e32 v73, 2, v72
	s_mov_b64 exec, vcc
	global_store_dword v73, v156, s[2:3]
	s_mov_b64 exec, -1
	s_andn2_b64 s[0:1], s[0:1], vcc
	s_cbranch_scc1 .Lsel_eq34
.Lsel_eqb34:
	v_cmp_lt_u32_e32 vcc, s44, v43
	v_cmp_le_u32_e64 s[0:1], s37, v43
	s_bcnt1_i32_b64 s4, vcc
	v_mbcnt_lo_u32_b32 v72, vcc_lo, v98
	v_mbcnt_hi_u32_b32 v72, vcc_hi, v72
	v_add_u32_e32 v98, s4, v98
	v_lshlrev_b32_e32 v73, 2, v72
	s_mov_b64 exec, vcc
	global_store_dword v73, v157, s[2:3]
	s_mov_b64 exec, -1
	s_andn2_b64 s[0:1], s[0:1], vcc
	s_cbranch_scc1 .Lsel_eq35
.Lsel_eqb35:
	v_cmp_lt_u32_e32 vcc, s44, v44
	v_cmp_le_u32_e64 s[0:1], s37, v44
	s_bcnt1_i32_b64 s4, vcc
	v_mbcnt_lo_u32_b32 v72, vcc_lo, v98
	v_mbcnt_hi_u32_b32 v72, vcc_hi, v72
	v_add_u32_e32 v98, s4, v98
	v_lshlrev_b32_e32 v73, 2, v72
	s_mov_b64 exec, vcc
	global_store_dword v73, v158, s[2:3]
	s_mov_b64 exec, -1
	s_andn2_b64 s[0:1], s[0:1], vcc
	s_cbranch_scc1 .Lsel_eq36
.Lsel_eqb36:
	v_cmp_lt_u32_e32 vcc, s44, v45
	v_cmp_le_u32_e64 s[0:1], s37, v45
	s_bcnt1_i32_b64 s4, vcc
	v_mbcnt_lo_u32_b32 v72, vcc_lo, v98
	v_mbcnt_hi_u32_b32 v72, vcc_hi, v72
	v_add_u32_e32 v98, s4, v98
	v_lshlrev_b32_e32 v73, 2, v72
	s_mov_b64 exec, vcc
	global_store_dword v73, v159, s[2:3]
	s_mov_b64 exec, -1
	s_andn2_b64 s[0:1], s[0:1], vcc
	s_cbranch_scc1 .Lsel_eq37
.Lsel_eqb37:
	v_cmp_lt_u32_e32 vcc, s44, v46
	v_cmp_le_u32_e64 s[0:1], s37, v46
	s_bcnt1_i32_b64 s4, vcc
	v_mbcnt_lo_u32_b32 v72, vcc_lo, v98
	v_mbcnt_hi_u32_b32 v72, vcc_hi, v72
	v_add_u32_e32 v98, s4, v98
	v_lshlrev_b32_e32 v73, 2, v72
	s_mov_b64 exec, vcc
	global_store_dword v73, v160, s[2:3]
	s_mov_b64 exec, -1
	s_andn2_b64 s[0:1], s[0:1], vcc
	s_cbranch_scc1 .Lsel_eq38
.Lsel_eqb38:
	v_cmp_lt_u32_e32 vcc, s44, v47
	v_cmp_le_u32_e64 s[0:1], s37, v47
	s_bcnt1_i32_b64 s4, vcc
	v_mbcnt_lo_u32_b32 v72, vcc_lo, v98
	v_mbcnt_hi_u32_b32 v72, vcc_hi, v72
	v_add_u32_e32 v98, s4, v98
	v_lshlrev_b32_e32 v73, 2, v72
	s_mov_b64 exec, vcc
	global_store_dword v73, v161, s[2:3]
	s_mov_b64 exec, -1
	s_andn2_b64 s[0:1], s[0:1], vcc
	s_cbranch_scc1 .Lsel_eq39
.Lsel_eqb39:
	s_cmp_lt_i32 s38, 40
	s_cbranch_scc1 .Lsel_cp_done
	v_cmp_lt_u32_e32 vcc, s44, v48
	v_cmp_le_u32_e64 s[0:1], s37, v48
	s_bcnt1_i32_b64 s4, vcc
	v_mbcnt_lo_u32_b32 v72, vcc_lo, v98
	v_mbcnt_hi_u32_b32 v72, vcc_hi, v72
	v_add_u32_e32 v98, s4, v98
	v_lshlrev_b32_e32 v73, 2, v72
	s_mov_b64 exec, vcc
	global_store_dword v73, v162, s[2:3]
	s_mov_b64 exec, -1
	s_andn2_b64 s[0:1], s[0:1], vcc
	s_cbranch_scc1 .Lsel_eq40
.Lsel_eqb40:
	v_cmp_lt_u32_e32 vcc, s44, v49
	v_cmp_le_u32_e64 s[0:1], s37, v49
	s_bcnt1_i32_b64 s4, vcc
	v_mbcnt_lo_u32_b32 v72, vcc_lo, v98
	v_mbcnt_hi_u32_b32 v72, vcc_hi, v72
	v_add_u32_e32 v98, s4, v98
	v_lshlrev_b32_e32 v73, 2, v72
	s_mov_b64 exec, vcc
	global_store_dword v73, v163, s[2:3]
	s_mov_b64 exec, -1
	s_andn2_b64 s[0:1], s[0:1], vcc
	s_cbranch_scc1 .Lsel_eq41
.Lsel_eqb41:
	v_cmp_lt_u32_e32 vcc, s44, v50
	v_cmp_le_u32_e64 s[0:1], s37, v50
	s_bcnt1_i32_b64 s4, vcc
	v_mbcnt_lo_u32_b32 v72, vcc_lo, v98
	v_mbcnt_hi_u32_b32 v72, vcc_hi, v72
	v_add_u32_e32 v98, s4, v98
	v_lshlrev_b32_e32 v73, 2, v72
	s_mov_b64 exec, vcc
	global_store_dword v73, v164, s[2:3]
	s_mov_b64 exec, -1
	s_andn2_b64 s[0:1], s[0:1], vcc
	s_cbranch_scc1 .Lsel_eq42
.Lsel_eqb42:
	v_cmp_lt_u32_e32 vcc, s44, v51
	v_cmp_le_u32_e64 s[0:1], s37, v51
	s_bcnt1_i32_b64 s4, vcc
	v_mbcnt_lo_u32_b32 v72, vcc_lo, v98
	v_mbcnt_hi_u32_b32 v72, vcc_hi, v72
	v_add_u32_e32 v98, s4, v98
	v_lshlrev_b32_e32 v73, 2, v72
	s_mov_b64 exec, vcc
	global_store_dword v73, v166, s[2:3]
	s_mov_b64 exec, -1
	s_andn2_b64 s[0:1], s[0:1], vcc
	s_cbranch_scc1 .Lsel_eq43
.Lsel_eqb43:
	v_cmp_lt_u32_e32 vcc, s44, v52
	v_cmp_le_u32_e64 s[0:1], s37, v52
	s_bcnt1_i32_b64 s4, vcc
	v_mbcnt_lo_u32_b32 v72, vcc_lo, v98
	v_mbcnt_hi_u32_b32 v72, vcc_hi, v72
	v_add_u32_e32 v98, s4, v98
	v_lshlrev_b32_e32 v73, 2, v72
	s_mov_b64 exec, vcc
	global_store_dword v73, v168, s[2:3]
	s_mov_b64 exec, -1
	s_andn2_b64 s[0:1], s[0:1], vcc
	s_cbranch_scc1 .Lsel_eq44
.Lsel_eqb44:
	v_cmp_lt_u32_e32 vcc, s44, v53
	v_cmp_le_u32_e64 s[0:1], s37, v53
	s_bcnt1_i32_b64 s4, vcc
	v_mbcnt_lo_u32_b32 v72, vcc_lo, v98
	v_mbcnt_hi_u32_b32 v72, vcc_hi, v72
	v_add_u32_e32 v98, s4, v98
	v_lshlrev_b32_e32 v73, 2, v72
	s_mov_b64 exec, vcc
	global_store_dword v73, v169, s[2:3]
	s_mov_b64 exec, -1
	s_andn2_b64 s[0:1], s[0:1], vcc
	s_cbranch_scc1 .Lsel_eq45
.Lsel_eqb45:
	v_cmp_lt_u32_e32 vcc, s44, v54
	v_cmp_le_u32_e64 s[0:1], s37, v54
	s_bcnt1_i32_b64 s4, vcc
	v_mbcnt_lo_u32_b32 v72, vcc_lo, v98
	v_mbcnt_hi_u32_b32 v72, vcc_hi, v72
	v_add_u32_e32 v98, s4, v98
	v_lshlrev_b32_e32 v73, 2, v72
	s_mov_b64 exec, vcc
	global_store_dword v73, v170, s[2:3]
	s_mov_b64 exec, -1
	s_andn2_b64 s[0:1], s[0:1], vcc
	s_cbranch_scc1 .Lsel_eq46
.Lsel_eqb46:
	v_cmp_lt_u32_e32 vcc, s44, v55
	v_cmp_le_u32_e64 s[0:1], s37, v55
	s_bcnt1_i32_b64 s4, vcc
	v_mbcnt_lo_u32_b32 v72, vcc_lo, v98
	v_mbcnt_hi_u32_b32 v72, vcc_hi, v72
	v_add_u32_e32 v98, s4, v98
	v_lshlrev_b32_e32 v73, 2, v72
	s_mov_b64 exec, vcc
	global_store_dword v73, v172, s[2:3]
	s_mov_b64 exec, -1
	s_andn2_b64 s[0:1], s[0:1], vcc
	s_cbranch_scc1 .Lsel_eq47
.Lsel_eqb47:
	s_cmp_lt_i32 s38, 48
	s_cbranch_scc1 .Lsel_cp_done
	v_cmp_lt_u32_e32 vcc, s44, v56
	v_cmp_le_u32_e64 s[0:1], s37, v56
	s_bcnt1_i32_b64 s4, vcc
	v_mbcnt_lo_u32_b32 v72, vcc_lo, v98
	v_mbcnt_hi_u32_b32 v72, vcc_hi, v72
	v_add_u32_e32 v98, s4, v98
	v_lshlrev_b32_e32 v73, 2, v72
	s_mov_b64 exec, vcc
	global_store_dword v73, v173, s[2:3]
	s_mov_b64 exec, -1
	s_andn2_b64 s[0:1], s[0:1], vcc
	s_cbranch_scc1 .Lsel_eq48
.Lsel_eqb48:
	v_cmp_lt_u32_e32 vcc, s44, v57
	v_cmp_le_u32_e64 s[0:1], s37, v57
	s_bcnt1_i32_b64 s4, vcc
	v_mbcnt_lo_u32_b32 v72, vcc_lo, v98
	v_mbcnt_hi_u32_b32 v72, vcc_hi, v72
	v_add_u32_e32 v98, s4, v98
	v_lshlrev_b32_e32 v73, 2, v72
	s_mov_b64 exec, vcc
	global_store_dword v73, v174, s[2:3]
	s_mov_b64 exec, -1
	s_andn2_b64 s[0:1], s[0:1], vcc
	s_cbranch_scc1 .Lsel_eq49
.Lsel_eqb49:
	v_cmp_lt_u32_e32 vcc, s44, v58
	v_cmp_le_u32_e64 s[0:1], s37, v58
	s_bcnt1_i32_b64 s4, vcc
	v_mbcnt_lo_u32_b32 v72, vcc_lo, v98
	v_mbcnt_hi_u32_b32 v72, vcc_hi, v72
	v_add_u32_e32 v98, s4, v98
	v_lshlrev_b32_e32 v73, 2, v72
	s_mov_b64 exec, vcc
	global_store_dword v73, v176, s[2:3]
	s_mov_b64 exec, -1
	s_andn2_b64 s[0:1], s[0:1], vcc
	s_cbranch_scc1 .Lsel_eq50
.Lsel_eqb50:
	v_cmp_lt_u32_e32 vcc, s44, v59
	v_cmp_le_u32_e64 s[0:1], s37, v59
	s_bcnt1_i32_b64 s4, vcc
	v_mbcnt_lo_u32_b32 v72, vcc_lo, v98
	v_mbcnt_hi_u32_b32 v72, vcc_hi, v72
	v_add_u32_e32 v98, s4, v98
	v_lshlrev_b32_e32 v73, 2, v72
	s_mov_b64 exec, vcc
	global_store_dword v73, v177, s[2:3]
	s_mov_b64 exec, -1
	s_andn2_b64 s[0:1], s[0:1], vcc
	s_cbranch_scc1 .Lsel_eq51
.Lsel_eqb51:
	v_cmp_lt_u32_e32 vcc, s44, v60
	v_cmp_le_u32_e64 s[0:1], s37, v60
	s_bcnt1_i32_b64 s4, vcc
	v_mbcnt_lo_u32_b32 v72, vcc_lo, v98
	v_mbcnt_hi_u32_b32 v72, vcc_hi, v72
	v_add_u32_e32 v98, s4, v98
	v_lshlrev_b32_e32 v73, 2, v72
	s_mov_b64 exec, vcc
	global_store_dword v73, v191, s[2:3]
	s_mov_b64 exec, -1
	s_andn2_b64 s[0:1], s[0:1], vcc
	s_cbranch_scc1 .Lsel_eq52
.Lsel_eqb52:
	v_cmp_lt_u32_e32 vcc, s44, v61
	v_cmp_le_u32_e64 s[0:1], s37, v61
	s_bcnt1_i32_b64 s4, vcc
	v_mbcnt_lo_u32_b32 v72, vcc_lo, v98
	v_mbcnt_hi_u32_b32 v72, vcc_hi, v72
	v_add_u32_e32 v98, s4, v98
	v_lshlrev_b32_e32 v73, 2, v72
	s_mov_b64 exec, vcc
	global_store_dword v73, v192, s[2:3]
	s_mov_b64 exec, -1
	s_andn2_b64 s[0:1], s[0:1], vcc
	s_cbranch_scc1 .Lsel_eq53
.Lsel_eqb53:
	v_cmp_lt_u32_e32 vcc, s44, v62
	v_cmp_le_u32_e64 s[0:1], s37, v62
	s_bcnt1_i32_b64 s4, vcc
	v_mbcnt_lo_u32_b32 v72, vcc_lo, v98
	v_mbcnt_hi_u32_b32 v72, vcc_hi, v72
	v_add_u32_e32 v98, s4, v98
	v_lshlrev_b32_e32 v73, 2, v72
	s_mov_b64 exec, vcc
	global_store_dword v73, v193, s[2:3]
	s_mov_b64 exec, -1
	s_andn2_b64 s[0:1], s[0:1], vcc
	s_cbranch_scc1 .Lsel_eq54
.Lsel_eqb54:
	v_cmp_lt_u32_e32 vcc, s44, v63
	v_cmp_le_u32_e64 s[0:1], s37, v63
	s_bcnt1_i32_b64 s4, vcc
	v_mbcnt_lo_u32_b32 v72, vcc_lo, v98
	v_mbcnt_hi_u32_b32 v72, vcc_hi, v72
	v_add_u32_e32 v98, s4, v98
	v_lshlrev_b32_e32 v73, 2, v72
	s_mov_b64 exec, vcc
	global_store_dword v73, v194, s[2:3]
	s_mov_b64 exec, -1
	s_andn2_b64 s[0:1], s[0:1], vcc
	s_cbranch_scc1 .Lsel_eq55
.Lsel_eqb55:
	s_cmp_lt_i32 s38, 56
	s_cbranch_scc1 .Lsel_cp_done
	v_cmp_lt_u32_e32 vcc, s44, v64
	v_cmp_le_u32_e64 s[0:1], s37, v64
	s_bcnt1_i32_b64 s4, vcc
	v_mbcnt_lo_u32_b32 v72, vcc_lo, v98
	v_mbcnt_hi_u32_b32 v72, vcc_hi, v72
	v_add_u32_e32 v98, s4, v98
	v_lshlrev_b32_e32 v73, 2, v72
	s_mov_b64 exec, vcc
	global_store_dword v73, v195, s[2:3]
	s_mov_b64 exec, -1
	s_andn2_b64 s[0:1], s[0:1], vcc
	s_cbranch_scc1 .Lsel_eq56
.Lsel_eqb56:
	v_cmp_lt_u32_e32 vcc, s44, v65
	v_cmp_le_u32_e64 s[0:1], s37, v65
	s_bcnt1_i32_b64 s4, vcc
	v_mbcnt_lo_u32_b32 v72, vcc_lo, v98
	v_mbcnt_hi_u32_b32 v72, vcc_hi, v72
	v_add_u32_e32 v98, s4, v98
	v_lshlrev_b32_e32 v73, 2, v72
	s_mov_b64 exec, vcc
	global_store_dword v73, v196, s[2:3]
	s_mov_b64 exec, -1
	s_andn2_b64 s[0:1], s[0:1], vcc
	s_cbranch_scc1 .Lsel_eq57
.Lsel_eqb57:
	v_cmp_lt_u32_e32 vcc, s44, v66
	v_cmp_le_u32_e64 s[0:1], s37, v66
	s_bcnt1_i32_b64 s4, vcc
	v_mbcnt_lo_u32_b32 v72, vcc_lo, v98
	v_mbcnt_hi_u32_b32 v72, vcc_hi, v72
	v_add_u32_e32 v98, s4, v98
	v_lshlrev_b32_e32 v73, 2, v72
	s_mov_b64 exec, vcc
	global_store_dword v73, v197, s[2:3]
	s_mov_b64 exec, -1
	s_andn2_b64 s[0:1], s[0:1], vcc
	s_cbranch_scc1 .Lsel_eq58
.Lsel_eqb58:
	v_cmp_lt_u32_e32 vcc, s44, v67
	v_cmp_le_u32_e64 s[0:1], s37, v67
	s_bcnt1_i32_b64 s4, vcc
	v_mbcnt_lo_u32_b32 v72, vcc_lo, v98
	v_mbcnt_hi_u32_b32 v72, vcc_hi, v72
	v_add_u32_e32 v98, s4, v98
	v_lshlrev_b32_e32 v73, 2, v72
	s_mov_b64 exec, vcc
	global_store_dword v73, v198, s[2:3]
	s_mov_b64 exec, -1
	s_andn2_b64 s[0:1], s[0:1], vcc
	s_cbranch_scc1 .Lsel_eq59
.Lsel_eqb59:
	v_cmp_lt_u32_e32 vcc, s44, v68
	v_cmp_le_u32_e64 s[0:1], s37, v68
	s_bcnt1_i32_b64 s4, vcc
	v_mbcnt_lo_u32_b32 v72, vcc_lo, v98
	v_mbcnt_hi_u32_b32 v72, vcc_hi, v72
	v_add_u32_e32 v98, s4, v98
	v_lshlrev_b32_e32 v73, 2, v72
	s_mov_b64 exec, vcc
	global_store_dword v73, v199, s[2:3]
	s_mov_b64 exec, -1
	s_andn2_b64 s[0:1], s[0:1], vcc
	s_cbranch_scc1 .Lsel_eq60
.Lsel_eqb60:
	v_cmp_lt_u32_e32 vcc, s44, v69
	v_cmp_le_u32_e64 s[0:1], s37, v69
	s_bcnt1_i32_b64 s4, vcc
	v_mbcnt_lo_u32_b32 v72, vcc_lo, v98
	v_mbcnt_hi_u32_b32 v72, vcc_hi, v72
	v_add_u32_e32 v98, s4, v98
	v_lshlrev_b32_e32 v73, 2, v72
	s_mov_b64 exec, vcc
	global_store_dword v73, v200, s[2:3]
	s_mov_b64 exec, -1
	s_andn2_b64 s[0:1], s[0:1], vcc
	s_cbranch_scc1 .Lsel_eq61
.Lsel_eqb61:
	v_cmp_lt_u32_e32 vcc, s44, v70
	v_cmp_le_u32_e64 s[0:1], s37, v70
	s_bcnt1_i32_b64 s4, vcc
	v_mbcnt_lo_u32_b32 v72, vcc_lo, v98
	v_mbcnt_hi_u32_b32 v72, vcc_hi, v72
	v_add_u32_e32 v98, s4, v98
	v_lshlrev_b32_e32 v73, 2, v72
	s_mov_b64 exec, vcc
	global_store_dword v73, v201, s[2:3]
	s_mov_b64 exec, -1
	s_andn2_b64 s[0:1], s[0:1], vcc
	s_cbranch_scc1 .Lsel_eq62
.Lsel_eqb62:
	v_cmp_lt_u32_e32 vcc, s44, v71
	v_cmp_le_u32_e64 s[0:1], s37, v71
	s_bcnt1_i32_b64 s4, vcc
	v_mbcnt_lo_u32_b32 v72, vcc_lo, v98
	v_mbcnt_hi_u32_b32 v72, vcc_hi, v72
	v_add_u32_e32 v98, s4, v98
	v_lshlrev_b32_e32 v73, 2, v72
	s_mov_b64 exec, vcc
	global_store_dword v73, v202, s[2:3]
	s_mov_b64 exec, -1
	s_andn2_b64 s[0:1], s[0:1], vcc
	s_cbranch_scc1 .Lsel_eq63
.Lsel_eqb63:
.Lsel_cp_done:
	s_waitcnt lgkmcnt(0)
	v_readlane_b32 s56, v253, 17
	v_readlane_b32 s57, v253, 18
	v_readlane_b32 s68, v253, 19
	v_readlane_b32 s69, v253, 20
	v_readlane_b32 s84, v252, 48
	v_readlane_b32 s85, v252, 49
	v_readlane_b32 s86, v252, 50
	v_readlane_b32 s87, v252, 51
	v_readlane_b32 s88, v252, 52
	v_readlane_b32 s89, v252, 53
	v_readlane_b32 s90, v252, 54
	v_readlane_b32 s91, v252, 55
	s_mov_b32 s54, 0xf800000
	s_movk_i32 s53, 0x6640
	s_mov_b64 s[24:25], -1
	s_branch .LBB0_144
.Lsel_eq0:
	v_mbcnt_lo_u32_b32 v72, s0, v99
	v_mbcnt_hi_u32_b32 v72, s1, v72
	s_bcnt1_i32_b64 s4, s[0:1]
	v_cmp_gt_u32_e32 vcc, 0x100, v72
	v_lshlrev_b32_e32 v73, 2, v72
	v_add_u32_e32 v99, s4, v99
	s_and_b64 exec, vcc, s[0:1]
	global_store_dword v73, v34, s[2:3]
	s_mov_b64 exec, -1
	s_branch .Lsel_eqb0
.Lsel_eq1:
	v_mbcnt_lo_u32_b32 v72, s0, v99
	v_mbcnt_hi_u32_b32 v72, s1, v72
	s_bcnt1_i32_b64 s4, s[0:1]
	v_cmp_gt_u32_e32 vcc, 0x100, v72
	v_lshlrev_b32_e32 v73, 2, v72
	v_add_u32_e32 v99, s4, v99
	s_and_b64 exec, vcc, s[0:1]
	global_store_dword v73, v115, s[2:3]
	s_mov_b64 exec, -1
	s_branch .Lsel_eqb1
.Lsel_eq2:
	v_mbcnt_lo_u32_b32 v72, s0, v99
	v_mbcnt_hi_u32_b32 v72, s1, v72
	s_bcnt1_i32_b64 s4, s[0:1]
	v_cmp_gt_u32_e32 vcc, 0x100, v72
	v_lshlrev_b32_e32 v73, 2, v72
	v_add_u32_e32 v99, s4, v99
	s_and_b64 exec, vcc, s[0:1]
	global_store_dword v73, v116, s[2:3]
	s_mov_b64 exec, -1
	s_branch .Lsel_eqb2
.Lsel_eq3:
	v_mbcnt_lo_u32_b32 v72, s0, v99
	v_mbcnt_hi_u32_b32 v72, s1, v72
	s_bcnt1_i32_b64 s4, s[0:1]
	v_cmp_gt_u32_e32 vcc, 0x100, v72
	v_lshlrev_b32_e32 v73, 2, v72
	v_add_u32_e32 v99, s4, v99
	s_and_b64 exec, vcc, s[0:1]
	global_store_dword v73, v117, s[2:3]
	s_mov_b64 exec, -1
	s_branch .Lsel_eqb3
.Lsel_eq4:
	v_mbcnt_lo_u32_b32 v72, s0, v99
	v_mbcnt_hi_u32_b32 v72, s1, v72
	s_bcnt1_i32_b64 s4, s[0:1]
	v_cmp_gt_u32_e32 vcc, 0x100, v72
	v_lshlrev_b32_e32 v73, 2, v72
	v_add_u32_e32 v99, s4, v99
	s_and_b64 exec, vcc, s[0:1]
	global_store_dword v73, v118, s[2:3]
	s_mov_b64 exec, -1
	s_branch .Lsel_eqb4
.Lsel_eq5:
	v_mbcnt_lo_u32_b32 v72, s0, v99
	v_mbcnt_hi_u32_b32 v72, s1, v72
	s_bcnt1_i32_b64 s4, s[0:1]
	v_cmp_gt_u32_e32 vcc, 0x100, v72
	v_lshlrev_b32_e32 v73, 2, v72
	v_add_u32_e32 v99, s4, v99
	s_and_b64 exec, vcc, s[0:1]
	global_store_dword v73, v119, s[2:3]
	s_mov_b64 exec, -1
	s_branch .Lsel_eqb5
.Lsel_eq6:
	v_mbcnt_lo_u32_b32 v72, s0, v99
	v_mbcnt_hi_u32_b32 v72, s1, v72
	s_bcnt1_i32_b64 s4, s[0:1]
	v_cmp_gt_u32_e32 vcc, 0x100, v72
	v_lshlrev_b32_e32 v73, 2, v72
	v_add_u32_e32 v99, s4, v99
	s_and_b64 exec, vcc, s[0:1]
	global_store_dword v73, v120, s[2:3]
	s_mov_b64 exec, -1
	s_branch .Lsel_eqb6
.Lsel_eq7:
	v_mbcnt_lo_u32_b32 v72, s0, v99
	v_mbcnt_hi_u32_b32 v72, s1, v72
	s_bcnt1_i32_b64 s4, s[0:1]
	v_cmp_gt_u32_e32 vcc, 0x100, v72
	v_lshlrev_b32_e32 v73, 2, v72
	v_add_u32_e32 v99, s4, v99
	s_and_b64 exec, vcc, s[0:1]
	global_store_dword v73, v121, s[2:3]
	s_mov_b64 exec, -1
	s_branch .Lsel_eqb7
.Lsel_eq8:
	v_mbcnt_lo_u32_b32 v72, s0, v99
	v_mbcnt_hi_u32_b32 v72, s1, v72
	s_bcnt1_i32_b64 s4, s[0:1]
	v_cmp_gt_u32_e32 vcc, 0x100, v72
	v_lshlrev_b32_e32 v73, 2, v72
	v_add_u32_e32 v99, s4, v99
	s_and_b64 exec, vcc, s[0:1]
	global_store_dword v73, v122, s[2:3]
	s_mov_b64 exec, -1
	s_branch .Lsel_eqb8
.Lsel_eq9:
	v_mbcnt_lo_u32_b32 v72, s0, v99
	v_mbcnt_hi_u32_b32 v72, s1, v72
	s_bcnt1_i32_b64 s4, s[0:1]
	v_cmp_gt_u32_e32 vcc, 0x100, v72
	v_lshlrev_b32_e32 v73, 2, v72
	v_add_u32_e32 v99, s4, v99
	s_and_b64 exec, vcc, s[0:1]
	global_store_dword v73, v123, s[2:3]
	s_mov_b64 exec, -1
	s_branch .Lsel_eqb9
.Lsel_eq10:
	v_mbcnt_lo_u32_b32 v72, s0, v99
	v_mbcnt_hi_u32_b32 v72, s1, v72
	s_bcnt1_i32_b64 s4, s[0:1]
	v_cmp_gt_u32_e32 vcc, 0x100, v72
	v_lshlrev_b32_e32 v73, 2, v72
	v_add_u32_e32 v99, s4, v99
	s_and_b64 exec, vcc, s[0:1]
	global_store_dword v73, v124, s[2:3]
	s_mov_b64 exec, -1
	s_branch .Lsel_eqb10
.Lsel_eq11:
	v_mbcnt_lo_u32_b32 v72, s0, v99
	v_mbcnt_hi_u32_b32 v72, s1, v72
	s_bcnt1_i32_b64 s4, s[0:1]
	v_cmp_gt_u32_e32 vcc, 0x100, v72
	v_lshlrev_b32_e32 v73, 2, v72
	v_add_u32_e32 v99, s4, v99
	s_and_b64 exec, vcc, s[0:1]
	global_store_dword v73, v125, s[2:3]
	s_mov_b64 exec, -1
	s_branch .Lsel_eqb11
.Lsel_eq12:
	v_mbcnt_lo_u32_b32 v72, s0, v99
	v_mbcnt_hi_u32_b32 v72, s1, v72
	s_bcnt1_i32_b64 s4, s[0:1]
	v_cmp_gt_u32_e32 vcc, 0x100, v72
	v_lshlrev_b32_e32 v73, 2, v72
	v_add_u32_e32 v99, s4, v99
	s_and_b64 exec, vcc, s[0:1]
	global_store_dword v73, v126, s[2:3]
	s_mov_b64 exec, -1
	s_branch .Lsel_eqb12
.Lsel_eq13:
	v_mbcnt_lo_u32_b32 v72, s0, v99
	v_mbcnt_hi_u32_b32 v72, s1, v72
	s_bcnt1_i32_b64 s4, s[0:1]
	v_cmp_gt_u32_e32 vcc, 0x100, v72
	v_lshlrev_b32_e32 v73, 2, v72
	v_add_u32_e32 v99, s4, v99
	s_and_b64 exec, vcc, s[0:1]
	global_store_dword v73, v127, s[2:3]
	s_mov_b64 exec, -1
	s_branch .Lsel_eqb13
.Lsel_eq14:
	v_mbcnt_lo_u32_b32 v72, s0, v99
	v_mbcnt_hi_u32_b32 v72, s1, v72
	s_bcnt1_i32_b64 s4, s[0:1]
	v_cmp_gt_u32_e32 vcc, 0x100, v72
	v_lshlrev_b32_e32 v73, 2, v72
	v_add_u32_e32 v99, s4, v99
	s_and_b64 exec, vcc, s[0:1]
	global_store_dword v73, v128, s[2:3]
	s_mov_b64 exec, -1
	s_branch .Lsel_eqb14
.Lsel_eq15:
	v_mbcnt_lo_u32_b32 v72, s0, v99
	v_mbcnt_hi_u32_b32 v72, s1, v72
	s_bcnt1_i32_b64 s4, s[0:1]
	v_cmp_gt_u32_e32 vcc, 0x100, v72
	v_lshlrev_b32_e32 v73, 2, v72
	v_add_u32_e32 v99, s4, v99
	s_and_b64 exec, vcc, s[0:1]
	global_store_dword v73, v129, s[2:3]
	s_mov_b64 exec, -1
	s_branch .Lsel_eqb15
.Lsel_eq16:
	v_mbcnt_lo_u32_b32 v72, s0, v99
	v_mbcnt_hi_u32_b32 v72, s1, v72
	s_bcnt1_i32_b64 s4, s[0:1]
	v_cmp_gt_u32_e32 vcc, 0x100, v72
	v_lshlrev_b32_e32 v73, 2, v72
	v_add_u32_e32 v99, s4, v99
	s_and_b64 exec, vcc, s[0:1]
	global_store_dword v73, v130, s[2:3]
	s_mov_b64 exec, -1
	s_branch .Lsel_eqb16
.Lsel_eq17:
	v_mbcnt_lo_u32_b32 v72, s0, v99
	v_mbcnt_hi_u32_b32 v72, s1, v72
	s_bcnt1_i32_b64 s4, s[0:1]
	v_cmp_gt_u32_e32 vcc, 0x100, v72
	v_lshlrev_b32_e32 v73, 2, v72
	v_add_u32_e32 v99, s4, v99
	s_and_b64 exec, vcc, s[0:1]
	global_store_dword v73, v131, s[2:3]
	s_mov_b64 exec, -1
	s_branch .Lsel_eqb17
.Lsel_eq18:
	v_mbcnt_lo_u32_b32 v72, s0, v99
	v_mbcnt_hi_u32_b32 v72, s1, v72
	s_bcnt1_i32_b64 s4, s[0:1]
	v_cmp_gt_u32_e32 vcc, 0x100, v72
	v_lshlrev_b32_e32 v73, 2, v72
	v_add_u32_e32 v99, s4, v99
	s_and_b64 exec, vcc, s[0:1]
	global_store_dword v73, v132, s[2:3]
	s_mov_b64 exec, -1
	s_branch .Lsel_eqb18
.Lsel_eq19:
	v_mbcnt_lo_u32_b32 v72, s0, v99
	v_mbcnt_hi_u32_b32 v72, s1, v72
	s_bcnt1_i32_b64 s4, s[0:1]
	v_cmp_gt_u32_e32 vcc, 0x100, v72
	v_lshlrev_b32_e32 v73, 2, v72
	v_add_u32_e32 v99, s4, v99
	s_and_b64 exec, vcc, s[0:1]
	global_store_dword v73, v133, s[2:3]
	s_mov_b64 exec, -1
	s_branch .Lsel_eqb19
.Lsel_eq20:
	v_mbcnt_lo_u32_b32 v72, s0, v99
	v_mbcnt_hi_u32_b32 v72, s1, v72
	s_bcnt1_i32_b64 s4, s[0:1]
	v_cmp_gt_u32_e32 vcc, 0x100, v72
	v_lshlrev_b32_e32 v73, 2, v72
	v_add_u32_e32 v99, s4, v99
	s_and_b64 exec, vcc, s[0:1]
	global_store_dword v73, v134, s[2:3]
	s_mov_b64 exec, -1
	s_branch .Lsel_eqb20
.Lsel_eq21:
	v_mbcnt_lo_u32_b32 v72, s0, v99
	v_mbcnt_hi_u32_b32 v72, s1, v72
	s_bcnt1_i32_b64 s4, s[0:1]
	v_cmp_gt_u32_e32 vcc, 0x100, v72
	v_lshlrev_b32_e32 v73, 2, v72
	v_add_u32_e32 v99, s4, v99
	s_and_b64 exec, vcc, s[0:1]
	global_store_dword v73, v135, s[2:3]
	s_mov_b64 exec, -1
	s_branch .Lsel_eqb21
.Lsel_eq22:
	v_mbcnt_lo_u32_b32 v72, s0, v99
	v_mbcnt_hi_u32_b32 v72, s1, v72
	s_bcnt1_i32_b64 s4, s[0:1]
	v_cmp_gt_u32_e32 vcc, 0x100, v72
	v_lshlrev_b32_e32 v73, 2, v72
	v_add_u32_e32 v99, s4, v99
	s_and_b64 exec, vcc, s[0:1]
	global_store_dword v73, v144, s[2:3]
	s_mov_b64 exec, -1
	s_branch .Lsel_eqb22
.Lsel_eq23:
	v_mbcnt_lo_u32_b32 v72, s0, v99
	v_mbcnt_hi_u32_b32 v72, s1, v72
	s_bcnt1_i32_b64 s4, s[0:1]
	v_cmp_gt_u32_e32 vcc, 0x100, v72
	v_lshlrev_b32_e32 v73, 2, v72
	v_add_u32_e32 v99, s4, v99
	s_and_b64 exec, vcc, s[0:1]
	global_store_dword v73, v145, s[2:3]
	s_mov_b64 exec, -1
	s_branch .Lsel_eqb23
.Lsel_eq24:
	v_mbcnt_lo_u32_b32 v72, s0, v99
	v_mbcnt_hi_u32_b32 v72, s1, v72
	s_bcnt1_i32_b64 s4, s[0:1]
	v_cmp_gt_u32_e32 vcc, 0x100, v72
	v_lshlrev_b32_e32 v73, 2, v72
	v_add_u32_e32 v99, s4, v99
	s_and_b64 exec, vcc, s[0:1]
	global_store_dword v73, v146, s[2:3]
	s_mov_b64 exec, -1
	s_branch .Lsel_eqb24
.Lsel_eq25:
	v_mbcnt_lo_u32_b32 v72, s0, v99
	v_mbcnt_hi_u32_b32 v72, s1, v72
	s_bcnt1_i32_b64 s4, s[0:1]
	v_cmp_gt_u32_e32 vcc, 0x100, v72
	v_lshlrev_b32_e32 v73, 2, v72
	v_add_u32_e32 v99, s4, v99
	s_and_b64 exec, vcc, s[0:1]
	global_store_dword v73, v147, s[2:3]
	s_mov_b64 exec, -1
	s_branch .Lsel_eqb25
.Lsel_eq26:
	v_mbcnt_lo_u32_b32 v72, s0, v99
	v_mbcnt_hi_u32_b32 v72, s1, v72
	s_bcnt1_i32_b64 s4, s[0:1]
	v_cmp_gt_u32_e32 vcc, 0x100, v72
	v_lshlrev_b32_e32 v73, 2, v72
	v_add_u32_e32 v99, s4, v99
	s_and_b64 exec, vcc, s[0:1]
	global_store_dword v73, v148, s[2:3]
	s_mov_b64 exec, -1
	s_branch .Lsel_eqb26
.Lsel_eq27:
	v_mbcnt_lo_u32_b32 v72, s0, v99
	v_mbcnt_hi_u32_b32 v72, s1, v72
	s_bcnt1_i32_b64 s4, s[0:1]
	v_cmp_gt_u32_e32 vcc, 0x100, v72
	v_lshlrev_b32_e32 v73, 2, v72
	v_add_u32_e32 v99, s4, v99
	s_and_b64 exec, vcc, s[0:1]
	global_store_dword v73, v149, s[2:3]
	s_mov_b64 exec, -1
	s_branch .Lsel_eqb27
.Lsel_eq28:
	v_mbcnt_lo_u32_b32 v72, s0, v99
	v_mbcnt_hi_u32_b32 v72, s1, v72
	s_bcnt1_i32_b64 s4, s[0:1]
	v_cmp_gt_u32_e32 vcc, 0x100, v72
	v_lshlrev_b32_e32 v73, 2, v72
	v_add_u32_e32 v99, s4, v99
	s_and_b64 exec, vcc, s[0:1]
	global_store_dword v73, v150, s[2:3]
	s_mov_b64 exec, -1
	s_branch .Lsel_eqb28
.Lsel_eq29:
	v_mbcnt_lo_u32_b32 v72, s0, v99
	v_mbcnt_hi_u32_b32 v72, s1, v72
	s_bcnt1_i32_b64 s4, s[0:1]
	v_cmp_gt_u32_e32 vcc, 0x100, v72
	v_lshlrev_b32_e32 v73, 2, v72
	v_add_u32_e32 v99, s4, v99
	s_and_b64 exec, vcc, s[0:1]
	global_store_dword v73, v151, s[2:3]
	s_mov_b64 exec, -1
	s_branch .Lsel_eqb29
.Lsel_eq30:
	v_mbcnt_lo_u32_b32 v72, s0, v99
	v_mbcnt_hi_u32_b32 v72, s1, v72
	s_bcnt1_i32_b64 s4, s[0:1]
	v_cmp_gt_u32_e32 vcc, 0x100, v72
	v_lshlrev_b32_e32 v73, 2, v72
	v_add_u32_e32 v99, s4, v99
	s_and_b64 exec, vcc, s[0:1]
	global_store_dword v73, v152, s[2:3]
	s_mov_b64 exec, -1
	s_branch .Lsel_eqb30
.Lsel_eq31:
	v_mbcnt_lo_u32_b32 v72, s0, v99
	v_mbcnt_hi_u32_b32 v72, s1, v72
	s_bcnt1_i32_b64 s4, s[0:1]
	v_cmp_gt_u32_e32 vcc, 0x100, v72
	v_lshlrev_b32_e32 v73, 2, v72
	v_add_u32_e32 v99, s4, v99
	s_and_b64 exec, vcc, s[0:1]
	global_store_dword v73, v153, s[2:3]
	s_mov_b64 exec, -1
	s_branch .Lsel_eqb31
.Lsel_eq32:
	v_mbcnt_lo_u32_b32 v72, s0, v99
	v_mbcnt_hi_u32_b32 v72, s1, v72
	s_bcnt1_i32_b64 s4, s[0:1]
	v_cmp_gt_u32_e32 vcc, 0x100, v72
	v_lshlrev_b32_e32 v73, 2, v72
	v_add_u32_e32 v99, s4, v99
	s_and_b64 exec, vcc, s[0:1]
	global_store_dword v73, v154, s[2:3]
	s_mov_b64 exec, -1
	s_branch .Lsel_eqb32
.Lsel_eq33:
	v_mbcnt_lo_u32_b32 v72, s0, v99
	v_mbcnt_hi_u32_b32 v72, s1, v72
	s_bcnt1_i32_b64 s4, s[0:1]
	v_cmp_gt_u32_e32 vcc, 0x100, v72
	v_lshlrev_b32_e32 v73, 2, v72
	v_add_u32_e32 v99, s4, v99
	s_and_b64 exec, vcc, s[0:1]
	global_store_dword v73, v155, s[2:3]
	s_mov_b64 exec, -1
	s_branch .Lsel_eqb33
.Lsel_eq34:
	v_mbcnt_lo_u32_b32 v72, s0, v99
	v_mbcnt_hi_u32_b32 v72, s1, v72
	s_bcnt1_i32_b64 s4, s[0:1]
	v_cmp_gt_u32_e32 vcc, 0x100, v72
	v_lshlrev_b32_e32 v73, 2, v72
	v_add_u32_e32 v99, s4, v99
	s_and_b64 exec, vcc, s[0:1]
	global_store_dword v73, v156, s[2:3]
	s_mov_b64 exec, -1
	s_branch .Lsel_eqb34
.Lsel_eq35:
	v_mbcnt_lo_u32_b32 v72, s0, v99
	v_mbcnt_hi_u32_b32 v72, s1, v72
	s_bcnt1_i32_b64 s4, s[0:1]
	v_cmp_gt_u32_e32 vcc, 0x100, v72
	v_lshlrev_b32_e32 v73, 2, v72
	v_add_u32_e32 v99, s4, v99
	s_and_b64 exec, vcc, s[0:1]
	global_store_dword v73, v157, s[2:3]
	s_mov_b64 exec, -1
	s_branch .Lsel_eqb35
.Lsel_eq36:
	v_mbcnt_lo_u32_b32 v72, s0, v99
	v_mbcnt_hi_u32_b32 v72, s1, v72
	s_bcnt1_i32_b64 s4, s[0:1]
	v_cmp_gt_u32_e32 vcc, 0x100, v72
	v_lshlrev_b32_e32 v73, 2, v72
	v_add_u32_e32 v99, s4, v99
	s_and_b64 exec, vcc, s[0:1]
	global_store_dword v73, v158, s[2:3]
	s_mov_b64 exec, -1
	s_branch .Lsel_eqb36
.Lsel_eq37:
	v_mbcnt_lo_u32_b32 v72, s0, v99
	v_mbcnt_hi_u32_b32 v72, s1, v72
	s_bcnt1_i32_b64 s4, s[0:1]
	v_cmp_gt_u32_e32 vcc, 0x100, v72
	v_lshlrev_b32_e32 v73, 2, v72
	v_add_u32_e32 v99, s4, v99
	s_and_b64 exec, vcc, s[0:1]
	global_store_dword v73, v159, s[2:3]
	s_mov_b64 exec, -1
	s_branch .Lsel_eqb37
.Lsel_eq38:
	v_mbcnt_lo_u32_b32 v72, s0, v99
	v_mbcnt_hi_u32_b32 v72, s1, v72
	s_bcnt1_i32_b64 s4, s[0:1]
	v_cmp_gt_u32_e32 vcc, 0x100, v72
	v_lshlrev_b32_e32 v73, 2, v72
	v_add_u32_e32 v99, s4, v99
	s_and_b64 exec, vcc, s[0:1]
	global_store_dword v73, v160, s[2:3]
	s_mov_b64 exec, -1
	s_branch .Lsel_eqb38
.Lsel_eq39:
	v_mbcnt_lo_u32_b32 v72, s0, v99
	v_mbcnt_hi_u32_b32 v72, s1, v72
	s_bcnt1_i32_b64 s4, s[0:1]
	v_cmp_gt_u32_e32 vcc, 0x100, v72
	v_lshlrev_b32_e32 v73, 2, v72
	v_add_u32_e32 v99, s4, v99
	s_and_b64 exec, vcc, s[0:1]
	global_store_dword v73, v161, s[2:3]
	s_mov_b64 exec, -1
	s_branch .Lsel_eqb39
.Lsel_eq40:
	v_mbcnt_lo_u32_b32 v72, s0, v99
	v_mbcnt_hi_u32_b32 v72, s1, v72
	s_bcnt1_i32_b64 s4, s[0:1]
	v_cmp_gt_u32_e32 vcc, 0x100, v72
	v_lshlrev_b32_e32 v73, 2, v72
	v_add_u32_e32 v99, s4, v99
	s_and_b64 exec, vcc, s[0:1]
	global_store_dword v73, v162, s[2:3]
	s_mov_b64 exec, -1
	s_branch .Lsel_eqb40
.Lsel_eq41:
	v_mbcnt_lo_u32_b32 v72, s0, v99
	v_mbcnt_hi_u32_b32 v72, s1, v72
	s_bcnt1_i32_b64 s4, s[0:1]
	v_cmp_gt_u32_e32 vcc, 0x100, v72
	v_lshlrev_b32_e32 v73, 2, v72
	v_add_u32_e32 v99, s4, v99
	s_and_b64 exec, vcc, s[0:1]
	global_store_dword v73, v163, s[2:3]
	s_mov_b64 exec, -1
	s_branch .Lsel_eqb41
.Lsel_eq42:
	v_mbcnt_lo_u32_b32 v72, s0, v99
	v_mbcnt_hi_u32_b32 v72, s1, v72
	s_bcnt1_i32_b64 s4, s[0:1]
	v_cmp_gt_u32_e32 vcc, 0x100, v72
	v_lshlrev_b32_e32 v73, 2, v72
	v_add_u32_e32 v99, s4, v99
	s_and_b64 exec, vcc, s[0:1]
	global_store_dword v73, v164, s[2:3]
	s_mov_b64 exec, -1
	s_branch .Lsel_eqb42
.Lsel_eq43:
	v_mbcnt_lo_u32_b32 v72, s0, v99
	v_mbcnt_hi_u32_b32 v72, s1, v72
	s_bcnt1_i32_b64 s4, s[0:1]
	v_cmp_gt_u32_e32 vcc, 0x100, v72
	v_lshlrev_b32_e32 v73, 2, v72
	v_add_u32_e32 v99, s4, v99
	s_and_b64 exec, vcc, s[0:1]
	global_store_dword v73, v166, s[2:3]
	s_mov_b64 exec, -1
	s_branch .Lsel_eqb43
.Lsel_eq44:
	v_mbcnt_lo_u32_b32 v72, s0, v99
	v_mbcnt_hi_u32_b32 v72, s1, v72
	s_bcnt1_i32_b64 s4, s[0:1]
	v_cmp_gt_u32_e32 vcc, 0x100, v72
	v_lshlrev_b32_e32 v73, 2, v72
	v_add_u32_e32 v99, s4, v99
	s_and_b64 exec, vcc, s[0:1]
	global_store_dword v73, v168, s[2:3]
	s_mov_b64 exec, -1
	s_branch .Lsel_eqb44
.Lsel_eq45:
	v_mbcnt_lo_u32_b32 v72, s0, v99
	v_mbcnt_hi_u32_b32 v72, s1, v72
	s_bcnt1_i32_b64 s4, s[0:1]
	v_cmp_gt_u32_e32 vcc, 0x100, v72
	v_lshlrev_b32_e32 v73, 2, v72
	v_add_u32_e32 v99, s4, v99
	s_and_b64 exec, vcc, s[0:1]
	global_store_dword v73, v169, s[2:3]
	s_mov_b64 exec, -1
	s_branch .Lsel_eqb45
.Lsel_eq46:
	v_mbcnt_lo_u32_b32 v72, s0, v99
	v_mbcnt_hi_u32_b32 v72, s1, v72
	s_bcnt1_i32_b64 s4, s[0:1]
	v_cmp_gt_u32_e32 vcc, 0x100, v72
	v_lshlrev_b32_e32 v73, 2, v72
	v_add_u32_e32 v99, s4, v99
	s_and_b64 exec, vcc, s[0:1]
	global_store_dword v73, v170, s[2:3]
	s_mov_b64 exec, -1
	s_branch .Lsel_eqb46
.Lsel_eq47:
	v_mbcnt_lo_u32_b32 v72, s0, v99
	v_mbcnt_hi_u32_b32 v72, s1, v72
	s_bcnt1_i32_b64 s4, s[0:1]
	v_cmp_gt_u32_e32 vcc, 0x100, v72
	v_lshlrev_b32_e32 v73, 2, v72
	v_add_u32_e32 v99, s4, v99
	s_and_b64 exec, vcc, s[0:1]
	global_store_dword v73, v172, s[2:3]
	s_mov_b64 exec, -1
	s_branch .Lsel_eqb47
.Lsel_eq48:
	v_mbcnt_lo_u32_b32 v72, s0, v99
	v_mbcnt_hi_u32_b32 v72, s1, v72
	s_bcnt1_i32_b64 s4, s[0:1]
	v_cmp_gt_u32_e32 vcc, 0x100, v72
	v_lshlrev_b32_e32 v73, 2, v72
	v_add_u32_e32 v99, s4, v99
	s_and_b64 exec, vcc, s[0:1]
	global_store_dword v73, v173, s[2:3]
	s_mov_b64 exec, -1
	s_branch .Lsel_eqb48
.Lsel_eq49:
	v_mbcnt_lo_u32_b32 v72, s0, v99
	v_mbcnt_hi_u32_b32 v72, s1, v72
	s_bcnt1_i32_b64 s4, s[0:1]
	v_cmp_gt_u32_e32 vcc, 0x100, v72
	v_lshlrev_b32_e32 v73, 2, v72
	v_add_u32_e32 v99, s4, v99
	s_and_b64 exec, vcc, s[0:1]
	global_store_dword v73, v174, s[2:3]
	s_mov_b64 exec, -1
	s_branch .Lsel_eqb49
.Lsel_eq50:
	v_mbcnt_lo_u32_b32 v72, s0, v99
	v_mbcnt_hi_u32_b32 v72, s1, v72
	s_bcnt1_i32_b64 s4, s[0:1]
	v_cmp_gt_u32_e32 vcc, 0x100, v72
	v_lshlrev_b32_e32 v73, 2, v72
	v_add_u32_e32 v99, s4, v99
	s_and_b64 exec, vcc, s[0:1]
	global_store_dword v73, v176, s[2:3]
	s_mov_b64 exec, -1
	s_branch .Lsel_eqb50
.Lsel_eq51:
	v_mbcnt_lo_u32_b32 v72, s0, v99
	v_mbcnt_hi_u32_b32 v72, s1, v72
	s_bcnt1_i32_b64 s4, s[0:1]
	v_cmp_gt_u32_e32 vcc, 0x100, v72
	v_lshlrev_b32_e32 v73, 2, v72
	v_add_u32_e32 v99, s4, v99
	s_and_b64 exec, vcc, s[0:1]
	global_store_dword v73, v177, s[2:3]
	s_mov_b64 exec, -1
	s_branch .Lsel_eqb51
.Lsel_eq52:
	v_mbcnt_lo_u32_b32 v72, s0, v99
	v_mbcnt_hi_u32_b32 v72, s1, v72
	s_bcnt1_i32_b64 s4, s[0:1]
	v_cmp_gt_u32_e32 vcc, 0x100, v72
	v_lshlrev_b32_e32 v73, 2, v72
	v_add_u32_e32 v99, s4, v99
	s_and_b64 exec, vcc, s[0:1]
	global_store_dword v73, v191, s[2:3]
	s_mov_b64 exec, -1
	s_branch .Lsel_eqb52
.Lsel_eq53:
	v_mbcnt_lo_u32_b32 v72, s0, v99
	v_mbcnt_hi_u32_b32 v72, s1, v72
	s_bcnt1_i32_b64 s4, s[0:1]
	v_cmp_gt_u32_e32 vcc, 0x100, v72
	v_lshlrev_b32_e32 v73, 2, v72
	v_add_u32_e32 v99, s4, v99
	s_and_b64 exec, vcc, s[0:1]
	global_store_dword v73, v192, s[2:3]
	s_mov_b64 exec, -1
	s_branch .Lsel_eqb53
.Lsel_eq54:
	v_mbcnt_lo_u32_b32 v72, s0, v99
	v_mbcnt_hi_u32_b32 v72, s1, v72
	s_bcnt1_i32_b64 s4, s[0:1]
	v_cmp_gt_u32_e32 vcc, 0x100, v72
	v_lshlrev_b32_e32 v73, 2, v72
	v_add_u32_e32 v99, s4, v99
	s_and_b64 exec, vcc, s[0:1]
	global_store_dword v73, v193, s[2:3]
	s_mov_b64 exec, -1
	s_branch .Lsel_eqb54
.Lsel_eq55:
	v_mbcnt_lo_u32_b32 v72, s0, v99
	v_mbcnt_hi_u32_b32 v72, s1, v72
	s_bcnt1_i32_b64 s4, s[0:1]
	v_cmp_gt_u32_e32 vcc, 0x100, v72
	v_lshlrev_b32_e32 v73, 2, v72
	v_add_u32_e32 v99, s4, v99
	s_and_b64 exec, vcc, s[0:1]
	global_store_dword v73, v194, s[2:3]
	s_mov_b64 exec, -1
	s_branch .Lsel_eqb55
.Lsel_eq56:
	v_mbcnt_lo_u32_b32 v72, s0, v99
	v_mbcnt_hi_u32_b32 v72, s1, v72
	s_bcnt1_i32_b64 s4, s[0:1]
	v_cmp_gt_u32_e32 vcc, 0x100, v72
	v_lshlrev_b32_e32 v73, 2, v72
	v_add_u32_e32 v99, s4, v99
	s_and_b64 exec, vcc, s[0:1]
	global_store_dword v73, v195, s[2:3]
	s_mov_b64 exec, -1
	s_branch .Lsel_eqb56
.Lsel_eq57:
	v_mbcnt_lo_u32_b32 v72, s0, v99
	v_mbcnt_hi_u32_b32 v72, s1, v72
	s_bcnt1_i32_b64 s4, s[0:1]
	v_cmp_gt_u32_e32 vcc, 0x100, v72
	v_lshlrev_b32_e32 v73, 2, v72
	v_add_u32_e32 v99, s4, v99
	s_and_b64 exec, vcc, s[0:1]
	global_store_dword v73, v196, s[2:3]
	s_mov_b64 exec, -1
	s_branch .Lsel_eqb57
.Lsel_eq58:
	v_mbcnt_lo_u32_b32 v72, s0, v99
	v_mbcnt_hi_u32_b32 v72, s1, v72
	s_bcnt1_i32_b64 s4, s[0:1]
	v_cmp_gt_u32_e32 vcc, 0x100, v72
	v_lshlrev_b32_e32 v73, 2, v72
	v_add_u32_e32 v99, s4, v99
	s_and_b64 exec, vcc, s[0:1]
	global_store_dword v73, v197, s[2:3]
	s_mov_b64 exec, -1
	s_branch .Lsel_eqb58
.Lsel_eq59:
	v_mbcnt_lo_u32_b32 v72, s0, v99
	v_mbcnt_hi_u32_b32 v72, s1, v72
	s_bcnt1_i32_b64 s4, s[0:1]
	v_cmp_gt_u32_e32 vcc, 0x100, v72
	v_lshlrev_b32_e32 v73, 2, v72
	v_add_u32_e32 v99, s4, v99
	s_and_b64 exec, vcc, s[0:1]
	global_store_dword v73, v198, s[2:3]
	s_mov_b64 exec, -1
	s_branch .Lsel_eqb59
.Lsel_eq60:
	v_mbcnt_lo_u32_b32 v72, s0, v99
	v_mbcnt_hi_u32_b32 v72, s1, v72
	s_bcnt1_i32_b64 s4, s[0:1]
	v_cmp_gt_u32_e32 vcc, 0x100, v72
	v_lshlrev_b32_e32 v73, 2, v72
	v_add_u32_e32 v99, s4, v99
	s_and_b64 exec, vcc, s[0:1]
	global_store_dword v73, v199, s[2:3]
	s_mov_b64 exec, -1
	s_branch .Lsel_eqb60
.Lsel_eq61:
	v_mbcnt_lo_u32_b32 v72, s0, v99
	v_mbcnt_hi_u32_b32 v72, s1, v72
	s_bcnt1_i32_b64 s4, s[0:1]
	v_cmp_gt_u32_e32 vcc, 0x100, v72
	v_lshlrev_b32_e32 v73, 2, v72
	v_add_u32_e32 v99, s4, v99
	s_and_b64 exec, vcc, s[0:1]
	global_store_dword v73, v200, s[2:3]
	s_mov_b64 exec, -1
	s_branch .Lsel_eqb61
.Lsel_eq62:
	v_mbcnt_lo_u32_b32 v72, s0, v99
	v_mbcnt_hi_u32_b32 v72, s1, v72
	s_bcnt1_i32_b64 s4, s[0:1]
	v_cmp_gt_u32_e32 vcc, 0x100, v72
	v_lshlrev_b32_e32 v73, 2, v72
	v_add_u32_e32 v99, s4, v99
	s_and_b64 exec, vcc, s[0:1]
	global_store_dword v73, v201, s[2:3]
	s_mov_b64 exec, -1
	s_branch .Lsel_eqb62
.Lsel_eq63:
	v_mbcnt_lo_u32_b32 v72, s0, v99
	v_mbcnt_hi_u32_b32 v72, s1, v72
	s_bcnt1_i32_b64 s4, s[0:1]
	v_cmp_gt_u32_e32 vcc, 0x100, v72
	v_lshlrev_b32_e32 v73, 2, v72
	v_add_u32_e32 v99, s4, v99
	s_and_b64 exec, vcc, s[0:1]
	global_store_dword v73, v202, s[2:3]
	s_mov_b64 exec, -1
	s_branch .Lsel_eqb63

.LBB0_307:
	v_mov_b32_e32 v2, v202
	s_and_saveexec_b64 s[24:25], s[0:1]
	s_cbranch_execz .LBB0_144
	s_branch .LBB0_143
.LBB0_801:
	v_cndmask_b32_e64 v0, v34, -1, s[80:81]
	global_store_dword v204, v0, s[2:3]
	v_cndmask_b32_e64 v0, v115, -1, s[6:7]
	global_store_dword v204, v0, s[2:3] offset:256
	v_cndmask_b32_e64 v0, v116, -1, s[78:79]
	global_store_dword v204, v0, s[2:3] offset:512
	v_cndmask_b32_e64 v2, v117, -1, s[4:5]
	s_or_b64 s[0:1], s[0:1], exec
	v_mov_b32_e32 v0, v117
	s_and_saveexec_b64 s[24:25], s[0:1]
	s_cbranch_execz .LBB0_144
	s_branch .LBB0_143
